# P2a conv_branch rewritten: weights loaded once per thread, 4 items of loads in flight per batch (2 drained batches), instead of a vmcnt(0) after nearly every load; EpiWo/EpiMerge waits count younger l
# speedup vs baseline: 1.0424x; 1.0203x over previous
.LBB0_251:
	v_and_b32_e32 v3, 31, v7
	v_mov_b32_e32 v2, v7
	v_lshlrev_b32_e32 v4, 5, v3
	v_lshlrev_b32_e32 v3, 4, v3
	global_load_dwordx4 v[212:215], v4, s[0:1]
	global_load_dwordx4 v[216:219], v4, s[0:1] offset:16
	global_load_dwordx4 v[220:223], v4, s[0:1] offset:1024
	global_load_dwordx4 v[224:227], v4, s[0:1] offset:1040
	global_load_dwordx4 v[228:231], v4, s[0:1] offset:2048
	global_load_dwordx4 v[232:235], v4, s[0:1] offset:2064
	global_load_dwordx4 v[236:239], v4, s[4:5]
	global_load_dwordx4 v[240:243], v4, s[4:5] offset:16
	v_lshrrev_b32_e32 v38, 5, v2
	v_and_b32_e32 v39, 0x1fff, v38
	v_cmp_gt_u32_e32 vcc, 2, v39
	v_mad_u32_u24 v40, v38, s75, v3
	v_lshl_add_u32 v7, v38, 11, v3
	v_add_u32_e32 v2, s97, v2
	v_cndmask_b32_e64 v41, v205, 0, vcc
	v_cndmask_b32_e64 v6, 1.0, 0, vcc
	v_cmp_eq_u32_e32 vcc, 0, v39
	v_add_u32_e32 v41, v40, v41
	global_load_dwordx4 v[44:47], v41, s[36:37]
	global_load_dwordx4 v[48:51], v41, s[36:37] offset:1024
	v_cndmask_b32_e64 v41, v206, 0, vcc
	v_cndmask_b32_e64 v8, 1.0, 0, vcc
	v_add_u32_e32 v41, v40, v41
	global_load_dwordx4 v[52:55], v41, s[36:37]
	global_load_dwordx4 v[56:59], v41, s[36:37] offset:1024
	global_load_dwordx4 v[60:63], v40, s[36:37]
	global_load_dwordx4 v[64:67], v40, s[36:37] offset:1024
	global_load_dwordx4 v[68:71], v40, s[36:37] offset:512
	global_load_dwordx4 v[72:75], v40, s[36:37] offset:1536
	v_lshrrev_b32_e32 v38, 5, v2
	v_and_b32_e32 v39, 0x1fff, v38
	v_cmp_gt_u32_e32 vcc, 2, v39
	v_mad_u32_u24 v40, v38, s75, v3
	v_lshl_add_u32 v11, v38, 11, v3
	v_add_u32_e32 v2, s97, v2
	v_cndmask_b32_e64 v41, v205, 0, vcc
	v_cndmask_b32_e64 v10, 1.0, 0, vcc
	v_cmp_eq_u32_e32 vcc, 0, v39
	v_add_u32_e32 v41, v40, v41
	global_load_dwordx4 v[76:79], v41, s[36:37]
	global_load_dwordx4 v[80:83], v41, s[36:37] offset:1024
	v_cndmask_b32_e64 v41, v206, 0, vcc
	v_cndmask_b32_e64 v12, 1.0, 0, vcc
	v_add_u32_e32 v41, v40, v41
	global_load_dwordx4 v[84:87], v41, s[36:37]
	global_load_dwordx4 v[88:91], v41, s[36:37] offset:1024
	global_load_dwordx4 v[92:95], v40, s[36:37]
	global_load_dwordx4 v[96:99], v40, s[36:37] offset:1024
	global_load_dwordx4 v[100:103], v40, s[36:37] offset:512
	global_load_dwordx4 v[104:107], v40, s[36:37] offset:1536
	v_lshrrev_b32_e32 v38, 5, v2
	v_and_b32_e32 v39, 0x1fff, v38
	v_cmp_gt_u32_e32 vcc, 2, v39
	v_mad_u32_u24 v40, v38, s75, v3
	v_lshl_add_u32 v15, v38, 11, v3
	v_add_u32_e32 v2, s97, v2
	v_cndmask_b32_e64 v41, v205, 0, vcc
	v_cndmask_b32_e64 v14, 1.0, 0, vcc
	v_cmp_eq_u32_e32 vcc, 0, v39
	v_add_u32_e32 v41, v40, v41
	global_load_dwordx4 v[108:111], v41, s[36:37]
	global_load_dwordx4 v[112:115], v41, s[36:37] offset:1024
	v_cndmask_b32_e64 v41, v206, 0, vcc
	v_cndmask_b32_e64 v16, 1.0, 0, vcc
	v_add_u32_e32 v41, v40, v41
	global_load_dwordx4 v[116:119], v41, s[36:37]
	global_load_dwordx4 v[120:123], v41, s[36:37] offset:1024
	global_load_dwordx4 v[124:127], v40, s[36:37]
	global_load_dwordx4 v[128:131], v40, s[36:37] offset:1024
	global_load_dwordx4 v[132:135], v40, s[36:37] offset:512
	global_load_dwordx4 v[136:139], v40, s[36:37] offset:1536
	v_lshrrev_b32_e32 v38, 5, v2
	v_and_b32_e32 v39, 0x1fff, v38
	v_cmp_gt_u32_e32 vcc, 2, v39
	v_mad_u32_u24 v40, v38, s75, v3
	v_lshl_add_u32 v19, v38, 11, v3
	v_add_u32_e32 v2, s97, v2
	v_cndmask_b32_e64 v41, v205, 0, vcc
	v_cndmask_b32_e64 v18, 1.0, 0, vcc
	v_cmp_eq_u32_e32 vcc, 0, v39
	v_add_u32_e32 v41, v40, v41
	global_load_dwordx4 v[162:165], v41, s[36:37]
	global_load_dwordx4 v[166:169], v41, s[36:37] offset:1024
	v_cndmask_b32_e64 v41, v206, 0, vcc
	v_cndmask_b32_e64 v20, 1.0, 0, vcc
	v_add_u32_e32 v41, v40, v41
	global_load_dwordx4 v[170:173], v41, s[36:37]
	global_load_dwordx4 v[174:177], v41, s[36:37] offset:1024
	global_load_dwordx4 v[178:181], v40, s[36:37]
	global_load_dwordx4 v[182:185], v40, s[36:37] offset:1024
	global_load_dwordx4 v[186:189], v40, s[36:37] offset:512
	global_load_dwordx4 v[190:193], v40, s[36:37] offset:1536
	s_waitcnt vmcnt(0)
	v_lshlrev_b32_e32 v22, 16, v44
	v_and_b32_e32 v23, 0xffff0000, v44
	v_lshlrev_b32_e32 v24, 16, v45
	v_and_b32_e32 v25, 0xffff0000, v45
	v_lshlrev_b32_e32 v26, 16, v46
	v_and_b32_e32 v27, 0xffff0000, v46
	v_lshlrev_b32_e32 v28, 16, v47
	v_and_b32_e32 v29, 0xffff0000, v47
	v_lshlrev_b32_e32 v30, 16, v48
	v_and_b32_e32 v31, 0xffff0000, v48
	v_lshlrev_b32_e32 v32, 16, v49
	v_and_b32_e32 v33, 0xffff0000, v49
	v_lshlrev_b32_e32 v34, 16, v50
	v_and_b32_e32 v35, 0xffff0000, v50
	v_lshlrev_b32_e32 v36, 16, v51
	v_and_b32_e32 v37, 0xffff0000, v51
	v_pk_mul_f32 v[22:23], v[22:23], v[30:31]
	v_pk_mul_f32 v[24:25], v[24:25], v[32:33]
	v_pk_mul_f32 v[26:27], v[26:27], v[34:35]
	v_pk_mul_f32 v[28:29], v[28:29], v[36:37]
	v_pk_mul_f32 v[244:245], v[212:213], v[6:7] op_sel_hi:[1,0]
	v_pk_mul_f32 v[246:247], v[214:215], v[6:7] op_sel_hi:[1,0]
	v_pk_mul_f32 v[248:249], v[216:217], v[6:7] op_sel_hi:[1,0]
	v_pk_mul_f32 v[4:5], v[218:219], v[6:7] op_sel_hi:[1,0]
	v_pk_fma_f32 v[140:141], v[244:245], v[22:23], 0 op_sel_hi:[1,1,0]
	v_pk_fma_f32 v[142:143], v[246:247], v[24:25], 0 op_sel_hi:[1,1,0]
	v_pk_fma_f32 v[144:145], v[248:249], v[26:27], 0 op_sel_hi:[1,1,0]
	v_pk_fma_f32 v[194:195], v[4:5], v[28:29], 0 op_sel_hi:[1,1,0]
	v_lshlrev_b32_e32 v22, 16, v52
	v_and_b32_e32 v23, 0xffff0000, v52
	v_lshlrev_b32_e32 v24, 16, v53
	v_and_b32_e32 v25, 0xffff0000, v53
	v_lshlrev_b32_e32 v26, 16, v54
	v_and_b32_e32 v27, 0xffff0000, v54
	v_lshlrev_b32_e32 v28, 16, v55
	v_and_b32_e32 v29, 0xffff0000, v55
	v_lshlrev_b32_e32 v30, 16, v56
	v_and_b32_e32 v31, 0xffff0000, v56
	v_lshlrev_b32_e32 v32, 16, v57
	v_and_b32_e32 v33, 0xffff0000, v57
	v_lshlrev_b32_e32 v34, 16, v58
	v_and_b32_e32 v35, 0xffff0000, v58
	v_lshlrev_b32_e32 v36, 16, v59
	v_and_b32_e32 v37, 0xffff0000, v59
	v_pk_mul_f32 v[22:23], v[22:23], v[30:31]
	v_pk_mul_f32 v[24:25], v[24:25], v[32:33]
	v_pk_mul_f32 v[26:27], v[26:27], v[34:35]
	v_pk_mul_f32 v[28:29], v[28:29], v[36:37]
	v_pk_mul_f32 v[244:245], v[220:221], v[8:9] op_sel_hi:[1,0]
	v_pk_mul_f32 v[246:247], v[222:223], v[8:9] op_sel_hi:[1,0]
	v_pk_mul_f32 v[248:249], v[224:225], v[8:9] op_sel_hi:[1,0]
	v_pk_mul_f32 v[4:5], v[226:227], v[8:9] op_sel_hi:[1,0]
	v_pk_fma_f32 v[140:141], v[244:245], v[22:23], v[140:141]
	v_pk_fma_f32 v[142:143], v[246:247], v[24:25], v[142:143]
	v_pk_fma_f32 v[144:145], v[248:249], v[26:27], v[144:145]
	v_pk_fma_f32 v[194:195], v[4:5], v[28:29], v[194:195]
	v_lshlrev_b32_e32 v22, 16, v60
	v_and_b32_e32 v23, 0xffff0000, v60
	v_lshlrev_b32_e32 v24, 16, v61
	v_and_b32_e32 v25, 0xffff0000, v61
	v_lshlrev_b32_e32 v26, 16, v62
	v_and_b32_e32 v27, 0xffff0000, v62
	v_lshlrev_b32_e32 v28, 16, v63
	v_and_b32_e32 v29, 0xffff0000, v63
	v_lshlrev_b32_e32 v30, 16, v64
	v_and_b32_e32 v31, 0xffff0000, v64
	v_lshlrev_b32_e32 v32, 16, v65
	v_and_b32_e32 v33, 0xffff0000, v65
	v_lshlrev_b32_e32 v34, 16, v66
	v_and_b32_e32 v35, 0xffff0000, v66
	v_lshlrev_b32_e32 v36, 16, v67
	v_and_b32_e32 v37, 0xffff0000, v67
	v_pk_mul_f32 v[22:23], v[22:23], v[30:31]
	v_pk_mul_f32 v[24:25], v[24:25], v[32:33]
	v_pk_mul_f32 v[26:27], v[26:27], v[34:35]
	v_pk_mul_f32 v[28:29], v[28:29], v[36:37]
	v_pk_fma_f32 v[140:141], v[228:229], v[22:23], v[140:141]
	v_pk_fma_f32 v[142:143], v[230:231], v[24:25], v[142:143]
	v_pk_fma_f32 v[144:145], v[232:233], v[26:27], v[144:145]
	v_pk_fma_f32 v[194:195], v[234:235], v[28:29], v[194:195]
	v_pk_add_f32 v[140:141], v[236:237], v[140:141]
	v_pk_add_f32 v[142:143], v[238:239], v[142:143]
	v_pk_add_f32 v[144:145], v[240:241], v[144:145]
	v_pk_add_f32 v[194:195], v[242:243], v[194:195]
	v_lshlrev_b32_e32 v30, 16, v68
	v_and_b32_e32 v31, 0xffff0000, v68
	v_lshlrev_b32_e32 v32, 16, v69
	v_and_b32_e32 v33, 0xffff0000, v69
	v_lshlrev_b32_e32 v34, 16, v70
	v_and_b32_e32 v35, 0xffff0000, v70
	v_lshlrev_b32_e32 v36, 16, v71
	v_and_b32_e32 v37, 0xffff0000, v71
	v_lshlrev_b32_e32 v22, 16, v72
	v_and_b32_e32 v23, 0xffff0000, v72
	v_lshlrev_b32_e32 v24, 16, v73
	v_and_b32_e32 v25, 0xffff0000, v73
	v_lshlrev_b32_e32 v26, 16, v74
	v_and_b32_e32 v27, 0xffff0000, v74
	v_lshlrev_b32_e32 v28, 16, v75
	v_and_b32_e32 v29, 0xffff0000, v75
	v_pk_mul_f32 v[140:141], v[140:141], v[30:31]
	v_pk_mul_f32 v[142:143], v[142:143], v[32:33]
	v_pk_mul_f32 v[144:145], v[144:145], v[34:35]
	v_pk_mul_f32 v[194:195], v[194:195], v[36:37]
	v_mul_f32_e32 v30, 0xbfb8aa3b, v22
	v_mul_f32_e32 v31, 0xbfb8aa3b, v23
	v_mul_f32_e32 v32, 0xbfb8aa3b, v24
	v_mul_f32_e32 v33, 0xbfb8aa3b, v25
	v_mul_f32_e32 v34, 0xbfb8aa3b, v26
	v_mul_f32_e32 v35, 0xbfb8aa3b, v27
	v_mul_f32_e32 v36, 0xbfb8aa3b, v28
	v_mul_f32_e32 v37, 0xbfb8aa3b, v29
	v_exp_f32_e32 v30, v30
	v_exp_f32_e32 v31, v31
	v_exp_f32_e32 v32, v32
	v_exp_f32_e32 v33, v33
	v_exp_f32_e32 v34, v34
	v_exp_f32_e32 v35, v35
	v_exp_f32_e32 v36, v36
	v_exp_f32_e32 v37, v37
	v_add_f32_e32 v30, 1.0, v30
	v_add_f32_e32 v31, 1.0, v31
	v_add_f32_e32 v32, 1.0, v32
	v_add_f32_e32 v33, 1.0, v33
	v_add_f32_e32 v34, 1.0, v34
	v_add_f32_e32 v35, 1.0, v35
	v_add_f32_e32 v36, 1.0, v36
	v_add_f32_e32 v37, 1.0, v37
	v_rcp_f32_e32 v30, v30
	v_rcp_f32_e32 v31, v31
	v_rcp_f32_e32 v32, v32
	v_rcp_f32_e32 v33, v33
	v_rcp_f32_e32 v34, v34
	v_rcp_f32_e32 v35, v35
	v_rcp_f32_e32 v36, v36
	v_rcp_f32_e32 v37, v37
	v_pk_mul_f32 v[30:31], v[30:31], v[22:23]
	v_pk_mul_f32 v[32:33], v[32:33], v[24:25]
	v_pk_mul_f32 v[34:35], v[34:35], v[26:27]
	v_pk_mul_f32 v[36:37], v[36:37], v[28:29]
	v_pk_mul_f32 v[140:141], v[140:141], v[30:31]
	v_pk_mul_f32 v[142:143], v[142:143], v[32:33]
	v_pk_mul_f32 v[144:145], v[144:145], v[34:35]
	v_pk_mul_f32 v[194:195], v[194:195], v[36:37]
	v_cvt_pk_bf16_f32 v44, v140, v141
	v_cvt_pk_bf16_f32 v45, v142, v143
	v_cvt_pk_bf16_f32 v46, v144, v145
	v_cvt_pk_bf16_f32 v47, v194, v195
	global_store_dwordx4 v7, v[44:47], s[34:35]
	v_lshlrev_b32_e32 v22, 16, v76
	v_and_b32_e32 v23, 0xffff0000, v76
	v_lshlrev_b32_e32 v24, 16, v77
	v_and_b32_e32 v25, 0xffff0000, v77
	v_lshlrev_b32_e32 v26, 16, v78
	v_and_b32_e32 v27, 0xffff0000, v78
	v_lshlrev_b32_e32 v28, 16, v79
	v_and_b32_e32 v29, 0xffff0000, v79
	v_lshlrev_b32_e32 v30, 16, v80
	v_and_b32_e32 v31, 0xffff0000, v80
	v_lshlrev_b32_e32 v32, 16, v81
	v_and_b32_e32 v33, 0xffff0000, v81
	v_lshlrev_b32_e32 v34, 16, v82
	v_and_b32_e32 v35, 0xffff0000, v82
	v_lshlrev_b32_e32 v36, 16, v83
	v_and_b32_e32 v37, 0xffff0000, v83
	v_pk_mul_f32 v[22:23], v[22:23], v[30:31]
	v_pk_mul_f32 v[24:25], v[24:25], v[32:33]
	v_pk_mul_f32 v[26:27], v[26:27], v[34:35]
	v_pk_mul_f32 v[28:29], v[28:29], v[36:37]
	v_pk_mul_f32 v[244:245], v[212:213], v[10:11] op_sel_hi:[1,0]
	v_pk_mul_f32 v[246:247], v[214:215], v[10:11] op_sel_hi:[1,0]
	v_pk_mul_f32 v[248:249], v[216:217], v[10:11] op_sel_hi:[1,0]
	v_pk_mul_f32 v[4:5], v[218:219], v[10:11] op_sel_hi:[1,0]
	v_pk_fma_f32 v[140:141], v[244:245], v[22:23], 0 op_sel_hi:[1,1,0]
	v_pk_fma_f32 v[142:143], v[246:247], v[24:25], 0 op_sel_hi:[1,1,0]
	v_pk_fma_f32 v[144:145], v[248:249], v[26:27], 0 op_sel_hi:[1,1,0]
	v_pk_fma_f32 v[194:195], v[4:5], v[28:29], 0 op_sel_hi:[1,1,0]
	v_lshlrev_b32_e32 v22, 16, v84
	v_and_b32_e32 v23, 0xffff0000, v84
	v_lshlrev_b32_e32 v24, 16, v85
	v_and_b32_e32 v25, 0xffff0000, v85
	v_lshlrev_b32_e32 v26, 16, v86
	v_and_b32_e32 v27, 0xffff0000, v86
	v_lshlrev_b32_e32 v28, 16, v87
	v_and_b32_e32 v29, 0xffff0000, v87
	v_lshlrev_b32_e32 v30, 16, v88
	v_and_b32_e32 v31, 0xffff0000, v88
	v_lshlrev_b32_e32 v32, 16, v89
	v_and_b32_e32 v33, 0xffff0000, v89
	v_lshlrev_b32_e32 v34, 16, v90
	v_and_b32_e32 v35, 0xffff0000, v90
	v_lshlrev_b32_e32 v36, 16, v91
	v_and_b32_e32 v37, 0xffff0000, v91
	v_pk_mul_f32 v[22:23], v[22:23], v[30:31]
	v_pk_mul_f32 v[24:25], v[24:25], v[32:33]
	v_pk_mul_f32 v[26:27], v[26:27], v[34:35]
	v_pk_mul_f32 v[28:29], v[28:29], v[36:37]
	v_pk_mul_f32 v[244:245], v[220:221], v[12:13] op_sel_hi:[1,0]
	v_pk_mul_f32 v[246:247], v[222:223], v[12:13] op_sel_hi:[1,0]
	v_pk_mul_f32 v[248:249], v[224:225], v[12:13] op_sel_hi:[1,0]
	v_pk_mul_f32 v[4:5], v[226:227], v[12:13] op_sel_hi:[1,0]
	v_pk_fma_f32 v[140:141], v[244:245], v[22:23], v[140:141]
	v_pk_fma_f32 v[142:143], v[246:247], v[24:25], v[142:143]
	v_pk_fma_f32 v[144:145], v[248:249], v[26:27], v[144:145]
	v_pk_fma_f32 v[194:195], v[4:5], v[28:29], v[194:195]
	v_lshlrev_b32_e32 v22, 16, v92
	v_and_b32_e32 v23, 0xffff0000, v92
	v_lshlrev_b32_e32 v24, 16, v93
	v_and_b32_e32 v25, 0xffff0000, v93
	v_lshlrev_b32_e32 v26, 16, v94
	v_and_b32_e32 v27, 0xffff0000, v94
	v_lshlrev_b32_e32 v28, 16, v95
	v_and_b32_e32 v29, 0xffff0000, v95
	v_lshlrev_b32_e32 v30, 16, v96
	v_and_b32_e32 v31, 0xffff0000, v96
	v_lshlrev_b32_e32 v32, 16, v97
	v_and_b32_e32 v33, 0xffff0000, v97
	v_lshlrev_b32_e32 v34, 16, v98
	v_and_b32_e32 v35, 0xffff0000, v98
	v_lshlrev_b32_e32 v36, 16, v99
	v_and_b32_e32 v37, 0xffff0000, v99
	v_pk_mul_f32 v[22:23], v[22:23], v[30:31]
	v_pk_mul_f32 v[24:25], v[24:25], v[32:33]
	v_pk_mul_f32 v[26:27], v[26:27], v[34:35]
	v_pk_mul_f32 v[28:29], v[28:29], v[36:37]
	v_pk_fma_f32 v[140:141], v[228:229], v[22:23], v[140:141]
	v_pk_fma_f32 v[142:143], v[230:231], v[24:25], v[142:143]
	v_pk_fma_f32 v[144:145], v[232:233], v[26:27], v[144:145]
	v_pk_fma_f32 v[194:195], v[234:235], v[28:29], v[194:195]
	v_pk_add_f32 v[140:141], v[236:237], v[140:141]
	v_pk_add_f32 v[142:143], v[238:239], v[142:143]
	v_pk_add_f32 v[144:145], v[240:241], v[144:145]
	v_pk_add_f32 v[194:195], v[242:243], v[194:195]
	v_lshlrev_b32_e32 v30, 16, v100
	v_and_b32_e32 v31, 0xffff0000, v100
	v_lshlrev_b32_e32 v32, 16, v101
	v_and_b32_e32 v33, 0xffff0000, v101
	v_lshlrev_b32_e32 v34, 16, v102
	v_and_b32_e32 v35, 0xffff0000, v102
	v_lshlrev_b32_e32 v36, 16, v103
	v_and_b32_e32 v37, 0xffff0000, v103
	v_lshlrev_b32_e32 v22, 16, v104
	v_and_b32_e32 v23, 0xffff0000, v104
	v_lshlrev_b32_e32 v24, 16, v105
	v_and_b32_e32 v25, 0xffff0000, v105
	v_lshlrev_b32_e32 v26, 16, v106
	v_and_b32_e32 v27, 0xffff0000, v106
	v_lshlrev_b32_e32 v28, 16, v107
	v_and_b32_e32 v29, 0xffff0000, v107
	v_pk_mul_f32 v[140:141], v[140:141], v[30:31]
	v_pk_mul_f32 v[142:143], v[142:143], v[32:33]
	v_pk_mul_f32 v[144:145], v[144:145], v[34:35]
	v_pk_mul_f32 v[194:195], v[194:195], v[36:37]
	v_mul_f32_e32 v30, 0xbfb8aa3b, v22
	v_mul_f32_e32 v31, 0xbfb8aa3b, v23
	v_mul_f32_e32 v32, 0xbfb8aa3b, v24
	v_mul_f32_e32 v33, 0xbfb8aa3b, v25
	v_mul_f32_e32 v34, 0xbfb8aa3b, v26
	v_mul_f32_e32 v35, 0xbfb8aa3b, v27
	v_mul_f32_e32 v36, 0xbfb8aa3b, v28
	v_mul_f32_e32 v37, 0xbfb8aa3b, v29
	v_exp_f32_e32 v30, v30
	v_exp_f32_e32 v31, v31
	v_exp_f32_e32 v32, v32
	v_exp_f32_e32 v33, v33
	v_exp_f32_e32 v34, v34
	v_exp_f32_e32 v35, v35
	v_exp_f32_e32 v36, v36
	v_exp_f32_e32 v37, v37
	v_add_f32_e32 v30, 1.0, v30
	v_add_f32_e32 v31, 1.0, v31
	v_add_f32_e32 v32, 1.0, v32
	v_add_f32_e32 v33, 1.0, v33
	v_add_f32_e32 v34, 1.0, v34
	v_add_f32_e32 v35, 1.0, v35
	v_add_f32_e32 v36, 1.0, v36
	v_add_f32_e32 v37, 1.0, v37
	v_rcp_f32_e32 v30, v30
	v_rcp_f32_e32 v31, v31
	v_rcp_f32_e32 v32, v32
	v_rcp_f32_e32 v33, v33
	v_rcp_f32_e32 v34, v34
	v_rcp_f32_e32 v35, v35
	v_rcp_f32_e32 v36, v36
	v_rcp_f32_e32 v37, v37
	v_pk_mul_f32 v[30:31], v[30:31], v[22:23]
	v_pk_mul_f32 v[32:33], v[32:33], v[24:25]
	v_pk_mul_f32 v[34:35], v[34:35], v[26:27]
	v_pk_mul_f32 v[36:37], v[36:37], v[28:29]
	v_pk_mul_f32 v[140:141], v[140:141], v[30:31]
	v_pk_mul_f32 v[142:143], v[142:143], v[32:33]
	v_pk_mul_f32 v[144:145], v[144:145], v[34:35]
	v_pk_mul_f32 v[194:195], v[194:195], v[36:37]
	v_cvt_pk_bf16_f32 v76, v140, v141
	v_cvt_pk_bf16_f32 v77, v142, v143
	v_cvt_pk_bf16_f32 v78, v144, v145
	v_cvt_pk_bf16_f32 v79, v194, v195
	global_store_dwordx4 v11, v[76:79], s[34:35]
	v_lshlrev_b32_e32 v22, 16, v108
	v_and_b32_e32 v23, 0xffff0000, v108
	v_lshlrev_b32_e32 v24, 16, v109
	v_and_b32_e32 v25, 0xffff0000, v109
	v_lshlrev_b32_e32 v26, 16, v110
	v_and_b32_e32 v27, 0xffff0000, v110
	v_lshlrev_b32_e32 v28, 16, v111
	v_and_b32_e32 v29, 0xffff0000, v111
	v_lshlrev_b32_e32 v30, 16, v112
	v_and_b32_e32 v31, 0xffff0000, v112
	v_lshlrev_b32_e32 v32, 16, v113
	v_and_b32_e32 v33, 0xffff0000, v113
	v_lshlrev_b32_e32 v34, 16, v114
	v_and_b32_e32 v35, 0xffff0000, v114
	v_lshlrev_b32_e32 v36, 16, v115
	v_and_b32_e32 v37, 0xffff0000, v115
	v_pk_mul_f32 v[22:23], v[22:23], v[30:31]
	v_pk_mul_f32 v[24:25], v[24:25], v[32:33]
	v_pk_mul_f32 v[26:27], v[26:27], v[34:35]
	v_pk_mul_f32 v[28:29], v[28:29], v[36:37]
	v_pk_mul_f32 v[244:245], v[212:213], v[14:15] op_sel_hi:[1,0]
	v_pk_mul_f32 v[246:247], v[214:215], v[14:15] op_sel_hi:[1,0]
	v_pk_mul_f32 v[248:249], v[216:217], v[14:15] op_sel_hi:[1,0]
	v_pk_mul_f32 v[4:5], v[218:219], v[14:15] op_sel_hi:[1,0]
	v_pk_fma_f32 v[140:141], v[244:245], v[22:23], 0 op_sel_hi:[1,1,0]
	v_pk_fma_f32 v[142:143], v[246:247], v[24:25], 0 op_sel_hi:[1,1,0]
	v_pk_fma_f32 v[144:145], v[248:249], v[26:27], 0 op_sel_hi:[1,1,0]
	v_pk_fma_f32 v[194:195], v[4:5], v[28:29], 0 op_sel_hi:[1,1,0]
	v_lshlrev_b32_e32 v22, 16, v116
	v_and_b32_e32 v23, 0xffff0000, v116
	v_lshlrev_b32_e32 v24, 16, v117
	v_and_b32_e32 v25, 0xffff0000, v117
	v_lshlrev_b32_e32 v26, 16, v118
	v_and_b32_e32 v27, 0xffff0000, v118
	v_lshlrev_b32_e32 v28, 16, v119
	v_and_b32_e32 v29, 0xffff0000, v119
	v_lshlrev_b32_e32 v30, 16, v120
	v_and_b32_e32 v31, 0xffff0000, v120
	v_lshlrev_b32_e32 v32, 16, v121
	v_and_b32_e32 v33, 0xffff0000, v121
	v_lshlrev_b32_e32 v34, 16, v122
	v_and_b32_e32 v35, 0xffff0000, v122
	v_lshlrev_b32_e32 v36, 16, v123
	v_and_b32_e32 v37, 0xffff0000, v123
	v_pk_mul_f32 v[22:23], v[22:23], v[30:31]
	v_pk_mul_f32 v[24:25], v[24:25], v[32:33]
	v_pk_mul_f32 v[26:27], v[26:27], v[34:35]
	v_pk_mul_f32 v[28:29], v[28:29], v[36:37]
	v_pk_mul_f32 v[244:245], v[220:221], v[16:17] op_sel_hi:[1,0]
	v_pk_mul_f32 v[246:247], v[222:223], v[16:17] op_sel_hi:[1,0]
	v_pk_mul_f32 v[248:249], v[224:225], v[16:17] op_sel_hi:[1,0]
	v_pk_mul_f32 v[4:5], v[226:227], v[16:17] op_sel_hi:[1,0]
	v_pk_fma_f32 v[140:141], v[244:245], v[22:23], v[140:141]
	v_pk_fma_f32 v[142:143], v[246:247], v[24:25], v[142:143]
	v_pk_fma_f32 v[144:145], v[248:249], v[26:27], v[144:145]
	v_pk_fma_f32 v[194:195], v[4:5], v[28:29], v[194:195]
	v_lshlrev_b32_e32 v22, 16, v124
	v_and_b32_e32 v23, 0xffff0000, v124
	v_lshlrev_b32_e32 v24, 16, v125
	v_and_b32_e32 v25, 0xffff0000, v125
	v_lshlrev_b32_e32 v26, 16, v126
	v_and_b32_e32 v27, 0xffff0000, v126
	v_lshlrev_b32_e32 v28, 16, v127
	v_and_b32_e32 v29, 0xffff0000, v127
	v_lshlrev_b32_e32 v30, 16, v128
	v_and_b32_e32 v31, 0xffff0000, v128
	v_lshlrev_b32_e32 v32, 16, v129
	v_and_b32_e32 v33, 0xffff0000, v129
	v_lshlrev_b32_e32 v34, 16, v130
	v_and_b32_e32 v35, 0xffff0000, v130
	v_lshlrev_b32_e32 v36, 16, v131
	v_and_b32_e32 v37, 0xffff0000, v131
	v_pk_mul_f32 v[22:23], v[22:23], v[30:31]
	v_pk_mul_f32 v[24:25], v[24:25], v[32:33]
	v_pk_mul_f32 v[26:27], v[26:27], v[34:35]
	v_pk_mul_f32 v[28:29], v[28:29], v[36:37]
	v_pk_fma_f32 v[140:141], v[228:229], v[22:23], v[140:141]
	v_pk_fma_f32 v[142:143], v[230:231], v[24:25], v[142:143]
	v_pk_fma_f32 v[144:145], v[232:233], v[26:27], v[144:145]
	v_pk_fma_f32 v[194:195], v[234:235], v[28:29], v[194:195]
	v_pk_add_f32 v[140:141], v[236:237], v[140:141]
	v_pk_add_f32 v[142:143], v[238:239], v[142:143]
	v_pk_add_f32 v[144:145], v[240:241], v[144:145]
	v_pk_add_f32 v[194:195], v[242:243], v[194:195]
	v_lshlrev_b32_e32 v30, 16, v132
	v_and_b32_e32 v31, 0xffff0000, v132
	v_lshlrev_b32_e32 v32, 16, v133
	v_and_b32_e32 v33, 0xffff0000, v133
	v_lshlrev_b32_e32 v34, 16, v134
	v_and_b32_e32 v35, 0xffff0000, v134
	v_lshlrev_b32_e32 v36, 16, v135
	v_and_b32_e32 v37, 0xffff0000, v135
	v_lshlrev_b32_e32 v22, 16, v136
	v_and_b32_e32 v23, 0xffff0000, v136
	v_lshlrev_b32_e32 v24, 16, v137
	v_and_b32_e32 v25, 0xffff0000, v137
	v_lshlrev_b32_e32 v26, 16, v138
	v_and_b32_e32 v27, 0xffff0000, v138
	v_lshlrev_b32_e32 v28, 16, v139
	v_and_b32_e32 v29, 0xffff0000, v139
	v_pk_mul_f32 v[140:141], v[140:141], v[30:31]
	v_pk_mul_f32 v[142:143], v[142:143], v[32:33]
	v_pk_mul_f32 v[144:145], v[144:145], v[34:35]
	v_pk_mul_f32 v[194:195], v[194:195], v[36:37]
	v_mul_f32_e32 v30, 0xbfb8aa3b, v22
	v_mul_f32_e32 v31, 0xbfb8aa3b, v23
	v_mul_f32_e32 v32, 0xbfb8aa3b, v24
	v_mul_f32_e32 v33, 0xbfb8aa3b, v25
	v_mul_f32_e32 v34, 0xbfb8aa3b, v26
	v_mul_f32_e32 v35, 0xbfb8aa3b, v27
	v_mul_f32_e32 v36, 0xbfb8aa3b, v28
	v_mul_f32_e32 v37, 0xbfb8aa3b, v29
	v_exp_f32_e32 v30, v30
	v_exp_f32_e32 v31, v31
	v_exp_f32_e32 v32, v32
	v_exp_f32_e32 v33, v33
	v_exp_f32_e32 v34, v34
	v_exp_f32_e32 v35, v35
	v_exp_f32_e32 v36, v36
	v_exp_f32_e32 v37, v37
	v_add_f32_e32 v30, 1.0, v30
	v_add_f32_e32 v31, 1.0, v31
	v_add_f32_e32 v32, 1.0, v32
	v_add_f32_e32 v33, 1.0, v33
	v_add_f32_e32 v34, 1.0, v34
	v_add_f32_e32 v35, 1.0, v35
	v_add_f32_e32 v36, 1.0, v36
	v_add_f32_e32 v37, 1.0, v37
	v_rcp_f32_e32 v30, v30
	v_rcp_f32_e32 v31, v31
	v_rcp_f32_e32 v32, v32
	v_rcp_f32_e32 v33, v33
	v_rcp_f32_e32 v34, v34
	v_rcp_f32_e32 v35, v35
	v_rcp_f32_e32 v36, v36
	v_rcp_f32_e32 v37, v37
	v_pk_mul_f32 v[30:31], v[30:31], v[22:23]
	v_pk_mul_f32 v[32:33], v[32:33], v[24:25]
	v_pk_mul_f32 v[34:35], v[34:35], v[26:27]
	v_pk_mul_f32 v[36:37], v[36:37], v[28:29]
	v_pk_mul_f32 v[140:141], v[140:141], v[30:31]
	v_pk_mul_f32 v[142:143], v[142:143], v[32:33]
	v_pk_mul_f32 v[144:145], v[144:145], v[34:35]
	v_pk_mul_f32 v[194:195], v[194:195], v[36:37]
	v_cvt_pk_bf16_f32 v108, v140, v141
	v_cvt_pk_bf16_f32 v109, v142, v143
	v_cvt_pk_bf16_f32 v110, v144, v145
	v_cvt_pk_bf16_f32 v111, v194, v195
	global_store_dwordx4 v15, v[108:111], s[34:35]
	v_lshlrev_b32_e32 v22, 16, v162
	v_and_b32_e32 v23, 0xffff0000, v162
	v_lshlrev_b32_e32 v24, 16, v163
	v_and_b32_e32 v25, 0xffff0000, v163
	v_lshlrev_b32_e32 v26, 16, v164
	v_and_b32_e32 v27, 0xffff0000, v164
	v_lshlrev_b32_e32 v28, 16, v165
	v_and_b32_e32 v29, 0xffff0000, v165
	v_lshlrev_b32_e32 v30, 16, v166
	v_and_b32_e32 v31, 0xffff0000, v166
	v_lshlrev_b32_e32 v32, 16, v167
	v_and_b32_e32 v33, 0xffff0000, v167
	v_lshlrev_b32_e32 v34, 16, v168
	v_and_b32_e32 v35, 0xffff0000, v168
	v_lshlrev_b32_e32 v36, 16, v169
	v_and_b32_e32 v37, 0xffff0000, v169
	v_pk_mul_f32 v[22:23], v[22:23], v[30:31]
	v_pk_mul_f32 v[24:25], v[24:25], v[32:33]
	v_pk_mul_f32 v[26:27], v[26:27], v[34:35]
	v_pk_mul_f32 v[28:29], v[28:29], v[36:37]
	v_pk_mul_f32 v[244:245], v[212:213], v[18:19] op_sel_hi:[1,0]
	v_pk_mul_f32 v[246:247], v[214:215], v[18:19] op_sel_hi:[1,0]
	v_pk_mul_f32 v[248:249], v[216:217], v[18:19] op_sel_hi:[1,0]
	v_pk_mul_f32 v[4:5], v[218:219], v[18:19] op_sel_hi:[1,0]
	v_pk_fma_f32 v[140:141], v[244:245], v[22:23], 0 op_sel_hi:[1,1,0]
	v_pk_fma_f32 v[142:143], v[246:247], v[24:25], 0 op_sel_hi:[1,1,0]
	v_pk_fma_f32 v[144:145], v[248:249], v[26:27], 0 op_sel_hi:[1,1,0]
	v_pk_fma_f32 v[194:195], v[4:5], v[28:29], 0 op_sel_hi:[1,1,0]
	v_lshlrev_b32_e32 v22, 16, v170
	v_and_b32_e32 v23, 0xffff0000, v170
	v_lshlrev_b32_e32 v24, 16, v171
	v_and_b32_e32 v25, 0xffff0000, v171
	v_lshlrev_b32_e32 v26, 16, v172
	v_and_b32_e32 v27, 0xffff0000, v172
	v_lshlrev_b32_e32 v28, 16, v173
	v_and_b32_e32 v29, 0xffff0000, v173
	v_lshlrev_b32_e32 v30, 16, v174
	v_and_b32_e32 v31, 0xffff0000, v174
	v_lshlrev_b32_e32 v32, 16, v175
	v_and_b32_e32 v33, 0xffff0000, v175
	v_lshlrev_b32_e32 v34, 16, v176
	v_and_b32_e32 v35, 0xffff0000, v176
	v_lshlrev_b32_e32 v36, 16, v177
	v_and_b32_e32 v37, 0xffff0000, v177
	v_pk_mul_f32 v[22:23], v[22:23], v[30:31]
	v_pk_mul_f32 v[24:25], v[24:25], v[32:33]
	v_pk_mul_f32 v[26:27], v[26:27], v[34:35]
	v_pk_mul_f32 v[28:29], v[28:29], v[36:37]
	v_pk_mul_f32 v[244:245], v[220:221], v[20:21] op_sel_hi:[1,0]
	v_pk_mul_f32 v[246:247], v[222:223], v[20:21] op_sel_hi:[1,0]
	v_pk_mul_f32 v[248:249], v[224:225], v[20:21] op_sel_hi:[1,0]
	v_pk_mul_f32 v[4:5], v[226:227], v[20:21] op_sel_hi:[1,0]
	v_pk_fma_f32 v[140:141], v[244:245], v[22:23], v[140:141]
	v_pk_fma_f32 v[142:143], v[246:247], v[24:25], v[142:143]
	v_pk_fma_f32 v[144:145], v[248:249], v[26:27], v[144:145]
	v_pk_fma_f32 v[194:195], v[4:5], v[28:29], v[194:195]
	v_lshlrev_b32_e32 v22, 16, v178
	v_and_b32_e32 v23, 0xffff0000, v178
	v_lshlrev_b32_e32 v24, 16, v179
	v_and_b32_e32 v25, 0xffff0000, v179
	v_lshlrev_b32_e32 v26, 16, v180
	v_and_b32_e32 v27, 0xffff0000, v180
	v_lshlrev_b32_e32 v28, 16, v181
	v_and_b32_e32 v29, 0xffff0000, v181
	v_lshlrev_b32_e32 v30, 16, v182
	v_and_b32_e32 v31, 0xffff0000, v182
	v_lshlrev_b32_e32 v32, 16, v183
	v_and_b32_e32 v33, 0xffff0000, v183
	v_lshlrev_b32_e32 v34, 16, v184
	v_and_b32_e32 v35, 0xffff0000, v184
	v_lshlrev_b32_e32 v36, 16, v185
	v_and_b32_e32 v37, 0xffff0000, v185
	v_pk_mul_f32 v[22:23], v[22:23], v[30:31]
	v_pk_mul_f32 v[24:25], v[24:25], v[32:33]
	v_pk_mul_f32 v[26:27], v[26:27], v[34:35]
	v_pk_mul_f32 v[28:29], v[28:29], v[36:37]
	v_pk_fma_f32 v[140:141], v[228:229], v[22:23], v[140:141]
	v_pk_fma_f32 v[142:143], v[230:231], v[24:25], v[142:143]
	v_pk_fma_f32 v[144:145], v[232:233], v[26:27], v[144:145]
	v_pk_fma_f32 v[194:195], v[234:235], v[28:29], v[194:195]
	v_pk_add_f32 v[140:141], v[236:237], v[140:141]
	v_pk_add_f32 v[142:143], v[238:239], v[142:143]
	v_pk_add_f32 v[144:145], v[240:241], v[144:145]
	v_pk_add_f32 v[194:195], v[242:243], v[194:195]
	v_lshlrev_b32_e32 v30, 16, v186
	v_and_b32_e32 v31, 0xffff0000, v186
	v_lshlrev_b32_e32 v32, 16, v187
	v_and_b32_e32 v33, 0xffff0000, v187
	v_lshlrev_b32_e32 v34, 16, v188
	v_and_b32_e32 v35, 0xffff0000, v188
	v_lshlrev_b32_e32 v36, 16, v189
	v_and_b32_e32 v37, 0xffff0000, v189
	v_lshlrev_b32_e32 v22, 16, v190
	v_and_b32_e32 v23, 0xffff0000, v190
	v_lshlrev_b32_e32 v24, 16, v191
	v_and_b32_e32 v25, 0xffff0000, v191
	v_lshlrev_b32_e32 v26, 16, v192
	v_and_b32_e32 v27, 0xffff0000, v192
	v_lshlrev_b32_e32 v28, 16, v193
	v_and_b32_e32 v29, 0xffff0000, v193
	v_pk_mul_f32 v[140:141], v[140:141], v[30:31]
	v_pk_mul_f32 v[142:143], v[142:143], v[32:33]
	v_pk_mul_f32 v[144:145], v[144:145], v[34:35]
	v_pk_mul_f32 v[194:195], v[194:195], v[36:37]
	v_mul_f32_e32 v30, 0xbfb8aa3b, v22
	v_mul_f32_e32 v31, 0xbfb8aa3b, v23
	v_mul_f32_e32 v32, 0xbfb8aa3b, v24
	v_mul_f32_e32 v33, 0xbfb8aa3b, v25
	v_mul_f32_e32 v34, 0xbfb8aa3b, v26
	v_mul_f32_e32 v35, 0xbfb8aa3b, v27
	v_mul_f32_e32 v36, 0xbfb8aa3b, v28
	v_mul_f32_e32 v37, 0xbfb8aa3b, v29
	v_exp_f32_e32 v30, v30
	v_exp_f32_e32 v31, v31
	v_exp_f32_e32 v32, v32
	v_exp_f32_e32 v33, v33
	v_exp_f32_e32 v34, v34
	v_exp_f32_e32 v35, v35
	v_exp_f32_e32 v36, v36
	v_exp_f32_e32 v37, v37
	v_add_f32_e32 v30, 1.0, v30
	v_add_f32_e32 v31, 1.0, v31
	v_add_f32_e32 v32, 1.0, v32
	v_add_f32_e32 v33, 1.0, v33
	v_add_f32_e32 v34, 1.0, v34
	v_add_f32_e32 v35, 1.0, v35
	v_add_f32_e32 v36, 1.0, v36
	v_add_f32_e32 v37, 1.0, v37
	v_rcp_f32_e32 v30, v30
	v_rcp_f32_e32 v31, v31
	v_rcp_f32_e32 v32, v32
	v_rcp_f32_e32 v33, v33
	v_rcp_f32_e32 v34, v34
	v_rcp_f32_e32 v35, v35
	v_rcp_f32_e32 v36, v36
	v_rcp_f32_e32 v37, v37
	v_pk_mul_f32 v[30:31], v[30:31], v[22:23]
	v_pk_mul_f32 v[32:33], v[32:33], v[24:25]
	v_pk_mul_f32 v[34:35], v[34:35], v[26:27]
	v_pk_mul_f32 v[36:37], v[36:37], v[28:29]
	v_pk_mul_f32 v[140:141], v[140:141], v[30:31]
	v_pk_mul_f32 v[142:143], v[142:143], v[32:33]
	v_pk_mul_f32 v[144:145], v[144:145], v[34:35]
	v_pk_mul_f32 v[194:195], v[194:195], v[36:37]
	v_cvt_pk_bf16_f32 v162, v140, v141
	v_cvt_pk_bf16_f32 v163, v142, v143
	v_cvt_pk_bf16_f32 v164, v144, v145
	v_cvt_pk_bf16_f32 v165, v194, v195
	global_store_dwordx4 v19, v[162:165], s[34:35]
	s_waitcnt vmcnt(0)
	v_lshrrev_b32_e32 v38, 5, v2
	v_and_b32_e32 v39, 0x1fff, v38
	v_cmp_gt_u32_e32 vcc, 2, v39
	v_mad_u32_u24 v40, v38, s75, v3
	v_lshl_add_u32 v42, v38, 11, v3
	v_add_u32_e32 v2, s97, v2
	v_cndmask_b32_e64 v41, v205, 0, vcc
	v_cndmask_b32_e64 v6, 1.0, 0, vcc
	v_cmp_eq_u32_e32 vcc, 0, v39
	v_add_u32_e32 v41, v40, v41
	global_load_dwordx4 v[44:47], v41, s[36:37]
	global_load_dwordx4 v[48:51], v41, s[36:37] offset:1024
	v_cndmask_b32_e64 v41, v206, 0, vcc
	v_cndmask_b32_e64 v8, 1.0, 0, vcc
	v_add_u32_e32 v41, v40, v41
	global_load_dwordx4 v[52:55], v41, s[36:37]
	global_load_dwordx4 v[56:59], v41, s[36:37] offset:1024
	global_load_dwordx4 v[60:63], v40, s[36:37]
	global_load_dwordx4 v[64:67], v40, s[36:37] offset:1024
	global_load_dwordx4 v[68:71], v40, s[36:37] offset:512
	global_load_dwordx4 v[72:75], v40, s[36:37] offset:1536
	v_lshrrev_b32_e32 v38, 5, v2
	v_and_b32_e32 v39, 0x1fff, v38
	v_cmp_gt_u32_e32 vcc, 2, v39
	v_mad_u32_u24 v40, v38, s75, v3
	v_lshl_add_u32 v9, v38, 11, v3
	v_add_u32_e32 v2, s97, v2
	v_cndmask_b32_e64 v41, v205, 0, vcc
	v_cndmask_b32_e64 v10, 1.0, 0, vcc
	v_cmp_eq_u32_e32 vcc, 0, v39
	v_add_u32_e32 v41, v40, v41
	global_load_dwordx4 v[76:79], v41, s[36:37]
	global_load_dwordx4 v[80:83], v41, s[36:37] offset:1024
	v_cndmask_b32_e64 v41, v206, 0, vcc
	v_cndmask_b32_e64 v12, 1.0, 0, vcc
	v_add_u32_e32 v41, v40, v41
	global_load_dwordx4 v[84:87], v41, s[36:37]
	global_load_dwordx4 v[88:91], v41, s[36:37] offset:1024
	global_load_dwordx4 v[92:95], v40, s[36:37]
	global_load_dwordx4 v[96:99], v40, s[36:37] offset:1024
	global_load_dwordx4 v[100:103], v40, s[36:37] offset:512
	global_load_dwordx4 v[104:107], v40, s[36:37] offset:1536
	v_lshrrev_b32_e32 v38, 5, v2
	v_and_b32_e32 v39, 0x1fff, v38
	v_cmp_gt_u32_e32 vcc, 2, v39
	v_mad_u32_u24 v40, v38, s75, v3
	v_lshl_add_u32 v13, v38, 11, v3
	v_add_u32_e32 v2, s97, v2
	v_cndmask_b32_e64 v41, v205, 0, vcc
	v_cndmask_b32_e64 v14, 1.0, 0, vcc
	v_cmp_eq_u32_e32 vcc, 0, v39
	v_add_u32_e32 v41, v40, v41
	global_load_dwordx4 v[108:111], v41, s[36:37]
	global_load_dwordx4 v[112:115], v41, s[36:37] offset:1024
	v_cndmask_b32_e64 v41, v206, 0, vcc
	v_cndmask_b32_e64 v16, 1.0, 0, vcc
	v_add_u32_e32 v41, v40, v41
	global_load_dwordx4 v[116:119], v41, s[36:37]
	global_load_dwordx4 v[120:123], v41, s[36:37] offset:1024
	global_load_dwordx4 v[124:127], v40, s[36:37]
	global_load_dwordx4 v[128:131], v40, s[36:37] offset:1024
	global_load_dwordx4 v[132:135], v40, s[36:37] offset:512
	global_load_dwordx4 v[136:139], v40, s[36:37] offset:1536
	v_lshrrev_b32_e32 v38, 5, v2
	v_and_b32_e32 v39, 0x1fff, v38
	v_cmp_gt_u32_e32 vcc, 2, v39
	v_mad_u32_u24 v40, v38, s75, v3
	v_lshl_add_u32 v17, v38, 11, v3
	v_add_u32_e32 v2, s97, v2
	v_cndmask_b32_e64 v41, v205, 0, vcc
	v_cndmask_b32_e64 v18, 1.0, 0, vcc
	v_cmp_eq_u32_e32 vcc, 0, v39
	v_add_u32_e32 v41, v40, v41
	global_load_dwordx4 v[162:165], v41, s[36:37]
	global_load_dwordx4 v[166:169], v41, s[36:37] offset:1024
	v_cndmask_b32_e64 v41, v206, 0, vcc
	v_cndmask_b32_e64 v20, 1.0, 0, vcc
	v_add_u32_e32 v41, v40, v41
	global_load_dwordx4 v[170:173], v41, s[36:37]
	global_load_dwordx4 v[174:177], v41, s[36:37] offset:1024
	global_load_dwordx4 v[178:181], v40, s[36:37]
	global_load_dwordx4 v[182:185], v40, s[36:37] offset:1024
	global_load_dwordx4 v[186:189], v40, s[36:37] offset:512
	global_load_dwordx4 v[190:193], v40, s[36:37] offset:1536
	s_waitcnt vmcnt(0)
	v_lshlrev_b32_e32 v22, 16, v44
	v_and_b32_e32 v23, 0xffff0000, v44
	v_lshlrev_b32_e32 v24, 16, v45
	v_and_b32_e32 v25, 0xffff0000, v45
	v_lshlrev_b32_e32 v26, 16, v46
	v_and_b32_e32 v27, 0xffff0000, v46
	v_lshlrev_b32_e32 v28, 16, v47
	v_and_b32_e32 v29, 0xffff0000, v47
	v_lshlrev_b32_e32 v30, 16, v48
	v_and_b32_e32 v31, 0xffff0000, v48
	v_lshlrev_b32_e32 v32, 16, v49
	v_and_b32_e32 v33, 0xffff0000, v49
	v_lshlrev_b32_e32 v34, 16, v50
	v_and_b32_e32 v35, 0xffff0000, v50
	v_lshlrev_b32_e32 v36, 16, v51
	v_and_b32_e32 v37, 0xffff0000, v51
	v_pk_mul_f32 v[22:23], v[22:23], v[30:31]
	v_pk_mul_f32 v[24:25], v[24:25], v[32:33]
	v_pk_mul_f32 v[26:27], v[26:27], v[34:35]
	v_pk_mul_f32 v[28:29], v[28:29], v[36:37]
	v_pk_mul_f32 v[244:245], v[212:213], v[6:7] op_sel_hi:[1,0]
	v_pk_mul_f32 v[246:247], v[214:215], v[6:7] op_sel_hi:[1,0]
	v_pk_mul_f32 v[248:249], v[216:217], v[6:7] op_sel_hi:[1,0]
	v_pk_mul_f32 v[4:5], v[218:219], v[6:7] op_sel_hi:[1,0]
	v_pk_fma_f32 v[140:141], v[244:245], v[22:23], 0 op_sel_hi:[1,1,0]
	v_pk_fma_f32 v[142:143], v[246:247], v[24:25], 0 op_sel_hi:[1,1,0]
	v_pk_fma_f32 v[144:145], v[248:249], v[26:27], 0 op_sel_hi:[1,1,0]
	v_pk_fma_f32 v[194:195], v[4:5], v[28:29], 0 op_sel_hi:[1,1,0]
	v_lshlrev_b32_e32 v22, 16, v52
	v_and_b32_e32 v23, 0xffff0000, v52
	v_lshlrev_b32_e32 v24, 16, v53
	v_and_b32_e32 v25, 0xffff0000, v53
	v_lshlrev_b32_e32 v26, 16, v54
	v_and_b32_e32 v27, 0xffff0000, v54
	v_lshlrev_b32_e32 v28, 16, v55
	v_and_b32_e32 v29, 0xffff0000, v55
	v_lshlrev_b32_e32 v30, 16, v56
	v_and_b32_e32 v31, 0xffff0000, v56
	v_lshlrev_b32_e32 v32, 16, v57
	v_and_b32_e32 v33, 0xffff0000, v57
	v_lshlrev_b32_e32 v34, 16, v58
	v_and_b32_e32 v35, 0xffff0000, v58
	v_lshlrev_b32_e32 v36, 16, v59
	v_and_b32_e32 v37, 0xffff0000, v59
	v_pk_mul_f32 v[22:23], v[22:23], v[30:31]
	v_pk_mul_f32 v[24:25], v[24:25], v[32:33]
	v_pk_mul_f32 v[26:27], v[26:27], v[34:35]
	v_pk_mul_f32 v[28:29], v[28:29], v[36:37]
	v_pk_mul_f32 v[244:245], v[220:221], v[8:9] op_sel_hi:[1,0]
	v_pk_mul_f32 v[246:247], v[222:223], v[8:9] op_sel_hi:[1,0]
	v_pk_mul_f32 v[248:249], v[224:225], v[8:9] op_sel_hi:[1,0]
	v_pk_mul_f32 v[4:5], v[226:227], v[8:9] op_sel_hi:[1,0]
	v_pk_fma_f32 v[140:141], v[244:245], v[22:23], v[140:141]
	v_pk_fma_f32 v[142:143], v[246:247], v[24:25], v[142:143]
	v_pk_fma_f32 v[144:145], v[248:249], v[26:27], v[144:145]
	v_pk_fma_f32 v[194:195], v[4:5], v[28:29], v[194:195]
	v_lshlrev_b32_e32 v22, 16, v60
	v_and_b32_e32 v23, 0xffff0000, v60
	v_lshlrev_b32_e32 v24, 16, v61
	v_and_b32_e32 v25, 0xffff0000, v61
	v_lshlrev_b32_e32 v26, 16, v62
	v_and_b32_e32 v27, 0xffff0000, v62
	v_lshlrev_b32_e32 v28, 16, v63
	v_and_b32_e32 v29, 0xffff0000, v63
	v_lshlrev_b32_e32 v30, 16, v64
	v_and_b32_e32 v31, 0xffff0000, v64
	v_lshlrev_b32_e32 v32, 16, v65
	v_and_b32_e32 v33, 0xffff0000, v65
	v_lshlrev_b32_e32 v34, 16, v66
	v_and_b32_e32 v35, 0xffff0000, v66
	v_lshlrev_b32_e32 v36, 16, v67
	v_and_b32_e32 v37, 0xffff0000, v67
	v_pk_mul_f32 v[22:23], v[22:23], v[30:31]
	v_pk_mul_f32 v[24:25], v[24:25], v[32:33]
	v_pk_mul_f32 v[26:27], v[26:27], v[34:35]
	v_pk_mul_f32 v[28:29], v[28:29], v[36:37]
	v_pk_fma_f32 v[140:141], v[228:229], v[22:23], v[140:141]
	v_pk_fma_f32 v[142:143], v[230:231], v[24:25], v[142:143]
	v_pk_fma_f32 v[144:145], v[232:233], v[26:27], v[144:145]
	v_pk_fma_f32 v[194:195], v[234:235], v[28:29], v[194:195]
	v_pk_add_f32 v[140:141], v[236:237], v[140:141]
	v_pk_add_f32 v[142:143], v[238:239], v[142:143]
	v_pk_add_f32 v[144:145], v[240:241], v[144:145]
	v_pk_add_f32 v[194:195], v[242:243], v[194:195]
	v_lshlrev_b32_e32 v30, 16, v68
	v_and_b32_e32 v31, 0xffff0000, v68
	v_lshlrev_b32_e32 v32, 16, v69
	v_and_b32_e32 v33, 0xffff0000, v69
	v_lshlrev_b32_e32 v34, 16, v70
	v_and_b32_e32 v35, 0xffff0000, v70
	v_lshlrev_b32_e32 v36, 16, v71
	v_and_b32_e32 v37, 0xffff0000, v71
	v_lshlrev_b32_e32 v22, 16, v72
	v_and_b32_e32 v23, 0xffff0000, v72
	v_lshlrev_b32_e32 v24, 16, v73
	v_and_b32_e32 v25, 0xffff0000, v73
	v_lshlrev_b32_e32 v26, 16, v74
	v_and_b32_e32 v27, 0xffff0000, v74
	v_lshlrev_b32_e32 v28, 16, v75
	v_and_b32_e32 v29, 0xffff0000, v75
	v_pk_mul_f32 v[140:141], v[140:141], v[30:31]
	v_pk_mul_f32 v[142:143], v[142:143], v[32:33]
	v_pk_mul_f32 v[144:145], v[144:145], v[34:35]
	v_pk_mul_f32 v[194:195], v[194:195], v[36:37]
	v_mul_f32_e32 v30, 0xbfb8aa3b, v22
	v_mul_f32_e32 v31, 0xbfb8aa3b, v23
	v_mul_f32_e32 v32, 0xbfb8aa3b, v24
	v_mul_f32_e32 v33, 0xbfb8aa3b, v25
	v_mul_f32_e32 v34, 0xbfb8aa3b, v26
	v_mul_f32_e32 v35, 0xbfb8aa3b, v27
	v_mul_f32_e32 v36, 0xbfb8aa3b, v28
	v_mul_f32_e32 v37, 0xbfb8aa3b, v29
	v_exp_f32_e32 v30, v30
	v_exp_f32_e32 v31, v31
	v_exp_f32_e32 v32, v32
	v_exp_f32_e32 v33, v33
	v_exp_f32_e32 v34, v34
	v_exp_f32_e32 v35, v35
	v_exp_f32_e32 v36, v36
	v_exp_f32_e32 v37, v37
	v_add_f32_e32 v30, 1.0, v30
	v_add_f32_e32 v31, 1.0, v31
	v_add_f32_e32 v32, 1.0, v32
	v_add_f32_e32 v33, 1.0, v33
	v_add_f32_e32 v34, 1.0, v34
	v_add_f32_e32 v35, 1.0, v35
	v_add_f32_e32 v36, 1.0, v36
	v_add_f32_e32 v37, 1.0, v37
	v_rcp_f32_e32 v30, v30
	v_rcp_f32_e32 v31, v31
	v_rcp_f32_e32 v32, v32
	v_rcp_f32_e32 v33, v33
	v_rcp_f32_e32 v34, v34
	v_rcp_f32_e32 v35, v35
	v_rcp_f32_e32 v36, v36
	v_rcp_f32_e32 v37, v37
	v_pk_mul_f32 v[30:31], v[30:31], v[22:23]
	v_pk_mul_f32 v[32:33], v[32:33], v[24:25]
	v_pk_mul_f32 v[34:35], v[34:35], v[26:27]
	v_pk_mul_f32 v[36:37], v[36:37], v[28:29]
	v_pk_mul_f32 v[140:141], v[140:141], v[30:31]
	v_pk_mul_f32 v[142:143], v[142:143], v[32:33]
	v_pk_mul_f32 v[144:145], v[144:145], v[34:35]
	v_pk_mul_f32 v[194:195], v[194:195], v[36:37]
	v_cvt_pk_bf16_f32 v44, v140, v141
	v_cvt_pk_bf16_f32 v45, v142, v143
	v_cvt_pk_bf16_f32 v46, v144, v145
	v_cvt_pk_bf16_f32 v47, v194, v195
	global_store_dwordx4 v42, v[44:47], s[34:35]
	v_lshlrev_b32_e32 v22, 16, v76
	v_and_b32_e32 v23, 0xffff0000, v76
	v_lshlrev_b32_e32 v24, 16, v77
	v_and_b32_e32 v25, 0xffff0000, v77
	v_lshlrev_b32_e32 v26, 16, v78
	v_and_b32_e32 v27, 0xffff0000, v78
	v_lshlrev_b32_e32 v28, 16, v79
	v_and_b32_e32 v29, 0xffff0000, v79
	v_lshlrev_b32_e32 v30, 16, v80
	v_and_b32_e32 v31, 0xffff0000, v80
	v_lshlrev_b32_e32 v32, 16, v81
	v_and_b32_e32 v33, 0xffff0000, v81
	v_lshlrev_b32_e32 v34, 16, v82
	v_and_b32_e32 v35, 0xffff0000, v82
	v_lshlrev_b32_e32 v36, 16, v83
	v_and_b32_e32 v37, 0xffff0000, v83
	v_pk_mul_f32 v[22:23], v[22:23], v[30:31]
	v_pk_mul_f32 v[24:25], v[24:25], v[32:33]
	v_pk_mul_f32 v[26:27], v[26:27], v[34:35]
	v_pk_mul_f32 v[28:29], v[28:29], v[36:37]
	v_pk_mul_f32 v[244:245], v[212:213], v[10:11] op_sel_hi:[1,0]
	v_pk_mul_f32 v[246:247], v[214:215], v[10:11] op_sel_hi:[1,0]
	v_pk_mul_f32 v[248:249], v[216:217], v[10:11] op_sel_hi:[1,0]
	v_pk_mul_f32 v[4:5], v[218:219], v[10:11] op_sel_hi:[1,0]
	v_pk_fma_f32 v[140:141], v[244:245], v[22:23], 0 op_sel_hi:[1,1,0]
	v_pk_fma_f32 v[142:143], v[246:247], v[24:25], 0 op_sel_hi:[1,1,0]
	v_pk_fma_f32 v[144:145], v[248:249], v[26:27], 0 op_sel_hi:[1,1,0]
	v_pk_fma_f32 v[194:195], v[4:5], v[28:29], 0 op_sel_hi:[1,1,0]
	v_lshlrev_b32_e32 v22, 16, v84
	v_and_b32_e32 v23, 0xffff0000, v84
	v_lshlrev_b32_e32 v24, 16, v85
	v_and_b32_e32 v25, 0xffff0000, v85
	v_lshlrev_b32_e32 v26, 16, v86
	v_and_b32_e32 v27, 0xffff0000, v86
	v_lshlrev_b32_e32 v28, 16, v87
	v_and_b32_e32 v29, 0xffff0000, v87
	v_lshlrev_b32_e32 v30, 16, v88
	v_and_b32_e32 v31, 0xffff0000, v88
	v_lshlrev_b32_e32 v32, 16, v89
	v_and_b32_e32 v33, 0xffff0000, v89
	v_lshlrev_b32_e32 v34, 16, v90
	v_and_b32_e32 v35, 0xffff0000, v90
	v_lshlrev_b32_e32 v36, 16, v91
	v_and_b32_e32 v37, 0xffff0000, v91
	v_pk_mul_f32 v[22:23], v[22:23], v[30:31]
	v_pk_mul_f32 v[24:25], v[24:25], v[32:33]
	v_pk_mul_f32 v[26:27], v[26:27], v[34:35]
	v_pk_mul_f32 v[28:29], v[28:29], v[36:37]
	v_pk_mul_f32 v[244:245], v[220:221], v[12:13] op_sel_hi:[1,0]
	v_pk_mul_f32 v[246:247], v[222:223], v[12:13] op_sel_hi:[1,0]
	v_pk_mul_f32 v[248:249], v[224:225], v[12:13] op_sel_hi:[1,0]
	v_pk_mul_f32 v[4:5], v[226:227], v[12:13] op_sel_hi:[1,0]
	v_pk_fma_f32 v[140:141], v[244:245], v[22:23], v[140:141]
	v_pk_fma_f32 v[142:143], v[246:247], v[24:25], v[142:143]
	v_pk_fma_f32 v[144:145], v[248:249], v[26:27], v[144:145]
	v_pk_fma_f32 v[194:195], v[4:5], v[28:29], v[194:195]
	v_lshlrev_b32_e32 v22, 16, v92
	v_and_b32_e32 v23, 0xffff0000, v92
	v_lshlrev_b32_e32 v24, 16, v93
	v_and_b32_e32 v25, 0xffff0000, v93
	v_lshlrev_b32_e32 v26, 16, v94
	v_and_b32_e32 v27, 0xffff0000, v94
	v_lshlrev_b32_e32 v28, 16, v95
	v_and_b32_e32 v29, 0xffff0000, v95
	v_lshlrev_b32_e32 v30, 16, v96
	v_and_b32_e32 v31, 0xffff0000, v96
	v_lshlrev_b32_e32 v32, 16, v97
	v_and_b32_e32 v33, 0xffff0000, v97
	v_lshlrev_b32_e32 v34, 16, v98
	v_and_b32_e32 v35, 0xffff0000, v98
	v_lshlrev_b32_e32 v36, 16, v99
	v_and_b32_e32 v37, 0xffff0000, v99
	v_pk_mul_f32 v[22:23], v[22:23], v[30:31]
	v_pk_mul_f32 v[24:25], v[24:25], v[32:33]
	v_pk_mul_f32 v[26:27], v[26:27], v[34:35]
	v_pk_mul_f32 v[28:29], v[28:29], v[36:37]
	v_pk_fma_f32 v[140:141], v[228:229], v[22:23], v[140:141]
	v_pk_fma_f32 v[142:143], v[230:231], v[24:25], v[142:143]
	v_pk_fma_f32 v[144:145], v[232:233], v[26:27], v[144:145]
	v_pk_fma_f32 v[194:195], v[234:235], v[28:29], v[194:195]
	v_pk_add_f32 v[140:141], v[236:237], v[140:141]
	v_pk_add_f32 v[142:143], v[238:239], v[142:143]
	v_pk_add_f32 v[144:145], v[240:241], v[144:145]
	v_pk_add_f32 v[194:195], v[242:243], v[194:195]
	v_lshlrev_b32_e32 v30, 16, v100
	v_and_b32_e32 v31, 0xffff0000, v100
	v_lshlrev_b32_e32 v32, 16, v101
	v_and_b32_e32 v33, 0xffff0000, v101
	v_lshlrev_b32_e32 v34, 16, v102
	v_and_b32_e32 v35, 0xffff0000, v102
	v_lshlrev_b32_e32 v36, 16, v103
	v_and_b32_e32 v37, 0xffff0000, v103
	v_lshlrev_b32_e32 v22, 16, v104
	v_and_b32_e32 v23, 0xffff0000, v104
	v_lshlrev_b32_e32 v24, 16, v105
	v_and_b32_e32 v25, 0xffff0000, v105
	v_lshlrev_b32_e32 v26, 16, v106
	v_and_b32_e32 v27, 0xffff0000, v106
	v_lshlrev_b32_e32 v28, 16, v107
	v_and_b32_e32 v29, 0xffff0000, v107
	v_pk_mul_f32 v[140:141], v[140:141], v[30:31]
	v_pk_mul_f32 v[142:143], v[142:143], v[32:33]
	v_pk_mul_f32 v[144:145], v[144:145], v[34:35]
	v_pk_mul_f32 v[194:195], v[194:195], v[36:37]
	v_mul_f32_e32 v30, 0xbfb8aa3b, v22
	v_mul_f32_e32 v31, 0xbfb8aa3b, v23
	v_mul_f32_e32 v32, 0xbfb8aa3b, v24
	v_mul_f32_e32 v33, 0xbfb8aa3b, v25
	v_mul_f32_e32 v34, 0xbfb8aa3b, v26
	v_mul_f32_e32 v35, 0xbfb8aa3b, v27
	v_mul_f32_e32 v36, 0xbfb8aa3b, v28
	v_mul_f32_e32 v37, 0xbfb8aa3b, v29
	v_exp_f32_e32 v30, v30
	v_exp_f32_e32 v31, v31
	v_exp_f32_e32 v32, v32
	v_exp_f32_e32 v33, v33
	v_exp_f32_e32 v34, v34
	v_exp_f32_e32 v35, v35
	v_exp_f32_e32 v36, v36
	v_exp_f32_e32 v37, v37
	v_add_f32_e32 v30, 1.0, v30
	v_add_f32_e32 v31, 1.0, v31
	v_add_f32_e32 v32, 1.0, v32
	v_add_f32_e32 v33, 1.0, v33
	v_add_f32_e32 v34, 1.0, v34
	v_add_f32_e32 v35, 1.0, v35
	v_add_f32_e32 v36, 1.0, v36
	v_add_f32_e32 v37, 1.0, v37
	v_rcp_f32_e32 v30, v30
	v_rcp_f32_e32 v31, v31
	v_rcp_f32_e32 v32, v32
	v_rcp_f32_e32 v33, v33
	v_rcp_f32_e32 v34, v34
	v_rcp_f32_e32 v35, v35
	v_rcp_f32_e32 v36, v36
	v_rcp_f32_e32 v37, v37
	v_pk_mul_f32 v[30:31], v[30:31], v[22:23]
	v_pk_mul_f32 v[32:33], v[32:33], v[24:25]
	v_pk_mul_f32 v[34:35], v[34:35], v[26:27]
	v_pk_mul_f32 v[36:37], v[36:37], v[28:29]
	v_pk_mul_f32 v[140:141], v[140:141], v[30:31]
	v_pk_mul_f32 v[142:143], v[142:143], v[32:33]
	v_pk_mul_f32 v[144:145], v[144:145], v[34:35]
	v_pk_mul_f32 v[194:195], v[194:195], v[36:37]
	v_cvt_pk_bf16_f32 v76, v140, v141
	v_cvt_pk_bf16_f32 v77, v142, v143
	v_cvt_pk_bf16_f32 v78, v144, v145
	v_cvt_pk_bf16_f32 v79, v194, v195
	global_store_dwordx4 v9, v[76:79], s[34:35]
	v_lshlrev_b32_e32 v22, 16, v108
	v_and_b32_e32 v23, 0xffff0000, v108
	v_lshlrev_b32_e32 v24, 16, v109
	v_and_b32_e32 v25, 0xffff0000, v109
	v_lshlrev_b32_e32 v26, 16, v110
	v_and_b32_e32 v27, 0xffff0000, v110
	v_lshlrev_b32_e32 v28, 16, v111
	v_and_b32_e32 v29, 0xffff0000, v111
	v_lshlrev_b32_e32 v30, 16, v112
	v_and_b32_e32 v31, 0xffff0000, v112
	v_lshlrev_b32_e32 v32, 16, v113
	v_and_b32_e32 v33, 0xffff0000, v113
	v_lshlrev_b32_e32 v34, 16, v114
	v_and_b32_e32 v35, 0xffff0000, v114
	v_lshlrev_b32_e32 v36, 16, v115
	v_and_b32_e32 v37, 0xffff0000, v115
	v_pk_mul_f32 v[22:23], v[22:23], v[30:31]
	v_pk_mul_f32 v[24:25], v[24:25], v[32:33]
	v_pk_mul_f32 v[26:27], v[26:27], v[34:35]
	v_pk_mul_f32 v[28:29], v[28:29], v[36:37]
	v_pk_mul_f32 v[244:245], v[212:213], v[14:15] op_sel_hi:[1,0]
	v_pk_mul_f32 v[246:247], v[214:215], v[14:15] op_sel_hi:[1,0]
	v_pk_mul_f32 v[248:249], v[216:217], v[14:15] op_sel_hi:[1,0]
	v_pk_mul_f32 v[4:5], v[218:219], v[14:15] op_sel_hi:[1,0]
	v_pk_fma_f32 v[140:141], v[244:245], v[22:23], 0 op_sel_hi:[1,1,0]
	v_pk_fma_f32 v[142:143], v[246:247], v[24:25], 0 op_sel_hi:[1,1,0]
	v_pk_fma_f32 v[144:145], v[248:249], v[26:27], 0 op_sel_hi:[1,1,0]
	v_pk_fma_f32 v[194:195], v[4:5], v[28:29], 0 op_sel_hi:[1,1,0]
	v_lshlrev_b32_e32 v22, 16, v116
	v_and_b32_e32 v23, 0xffff0000, v116
	v_lshlrev_b32_e32 v24, 16, v117
	v_and_b32_e32 v25, 0xffff0000, v117
	v_lshlrev_b32_e32 v26, 16, v118
	v_and_b32_e32 v27, 0xffff0000, v118
	v_lshlrev_b32_e32 v28, 16, v119
	v_and_b32_e32 v29, 0xffff0000, v119
	v_lshlrev_b32_e32 v30, 16, v120
	v_and_b32_e32 v31, 0xffff0000, v120
	v_lshlrev_b32_e32 v32, 16, v121
	v_and_b32_e32 v33, 0xffff0000, v121
	v_lshlrev_b32_e32 v34, 16, v122
	v_and_b32_e32 v35, 0xffff0000, v122
	v_lshlrev_b32_e32 v36, 16, v123
	v_and_b32_e32 v37, 0xffff0000, v123
	v_pk_mul_f32 v[22:23], v[22:23], v[30:31]
	v_pk_mul_f32 v[24:25], v[24:25], v[32:33]
	v_pk_mul_f32 v[26:27], v[26:27], v[34:35]
	v_pk_mul_f32 v[28:29], v[28:29], v[36:37]
	v_pk_mul_f32 v[244:245], v[220:221], v[16:17] op_sel_hi:[1,0]
	v_pk_mul_f32 v[246:247], v[222:223], v[16:17] op_sel_hi:[1,0]
	v_pk_mul_f32 v[248:249], v[224:225], v[16:17] op_sel_hi:[1,0]
	v_pk_mul_f32 v[4:5], v[226:227], v[16:17] op_sel_hi:[1,0]
	v_pk_fma_f32 v[140:141], v[244:245], v[22:23], v[140:141]
	v_pk_fma_f32 v[142:143], v[246:247], v[24:25], v[142:143]
	v_pk_fma_f32 v[144:145], v[248:249], v[26:27], v[144:145]
	v_pk_fma_f32 v[194:195], v[4:5], v[28:29], v[194:195]
	v_lshlrev_b32_e32 v22, 16, v124
	v_and_b32_e32 v23, 0xffff0000, v124
	v_lshlrev_b32_e32 v24, 16, v125
	v_and_b32_e32 v25, 0xffff0000, v125
	v_lshlrev_b32_e32 v26, 16, v126
	v_and_b32_e32 v27, 0xffff0000, v126
	v_lshlrev_b32_e32 v28, 16, v127
	v_and_b32_e32 v29, 0xffff0000, v127
	v_lshlrev_b32_e32 v30, 16, v128
	v_and_b32_e32 v31, 0xffff0000, v128
	v_lshlrev_b32_e32 v32, 16, v129
	v_and_b32_e32 v33, 0xffff0000, v129
	v_lshlrev_b32_e32 v34, 16, v130
	v_and_b32_e32 v35, 0xffff0000, v130
	v_lshlrev_b32_e32 v36, 16, v131
	v_and_b32_e32 v37, 0xffff0000, v131
	v_pk_mul_f32 v[22:23], v[22:23], v[30:31]
	v_pk_mul_f32 v[24:25], v[24:25], v[32:33]
	v_pk_mul_f32 v[26:27], v[26:27], v[34:35]
	v_pk_mul_f32 v[28:29], v[28:29], v[36:37]
	v_pk_fma_f32 v[140:141], v[228:229], v[22:23], v[140:141]
	v_pk_fma_f32 v[142:143], v[230:231], v[24:25], v[142:143]
	v_pk_fma_f32 v[144:145], v[232:233], v[26:27], v[144:145]
	v_pk_fma_f32 v[194:195], v[234:235], v[28:29], v[194:195]
	v_pk_add_f32 v[140:141], v[236:237], v[140:141]
	v_pk_add_f32 v[142:143], v[238:239], v[142:143]
	v_pk_add_f32 v[144:145], v[240:241], v[144:145]
	v_pk_add_f32 v[194:195], v[242:243], v[194:195]
	v_lshlrev_b32_e32 v30, 16, v132
	v_and_b32_e32 v31, 0xffff0000, v132
	v_lshlrev_b32_e32 v32, 16, v133
	v_and_b32_e32 v33, 0xffff0000, v133
	v_lshlrev_b32_e32 v34, 16, v134
	v_and_b32_e32 v35, 0xffff0000, v134
	v_lshlrev_b32_e32 v36, 16, v135
	v_and_b32_e32 v37, 0xffff0000, v135
	v_lshlrev_b32_e32 v22, 16, v136
	v_and_b32_e32 v23, 0xffff0000, v136
	v_lshlrev_b32_e32 v24, 16, v137
	v_and_b32_e32 v25, 0xffff0000, v137
	v_lshlrev_b32_e32 v26, 16, v138
	v_and_b32_e32 v27, 0xffff0000, v138
	v_lshlrev_b32_e32 v28, 16, v139
	v_and_b32_e32 v29, 0xffff0000, v139
	v_pk_mul_f32 v[140:141], v[140:141], v[30:31]
	v_pk_mul_f32 v[142:143], v[142:143], v[32:33]
	v_pk_mul_f32 v[144:145], v[144:145], v[34:35]
	v_pk_mul_f32 v[194:195], v[194:195], v[36:37]
	v_mul_f32_e32 v30, 0xbfb8aa3b, v22
	v_mul_f32_e32 v31, 0xbfb8aa3b, v23
	v_mul_f32_e32 v32, 0xbfb8aa3b, v24
	v_mul_f32_e32 v33, 0xbfb8aa3b, v25
	v_mul_f32_e32 v34, 0xbfb8aa3b, v26
	v_mul_f32_e32 v35, 0xbfb8aa3b, v27
	v_mul_f32_e32 v36, 0xbfb8aa3b, v28
	v_mul_f32_e32 v37, 0xbfb8aa3b, v29
	v_exp_f32_e32 v30, v30
	v_exp_f32_e32 v31, v31
	v_exp_f32_e32 v32, v32
	v_exp_f32_e32 v33, v33
	v_exp_f32_e32 v34, v34
	v_exp_f32_e32 v35, v35
	v_exp_f32_e32 v36, v36
	v_exp_f32_e32 v37, v37
	v_add_f32_e32 v30, 1.0, v30
	v_add_f32_e32 v31, 1.0, v31
	v_add_f32_e32 v32, 1.0, v32
	v_add_f32_e32 v33, 1.0, v33
	v_add_f32_e32 v34, 1.0, v34
	v_add_f32_e32 v35, 1.0, v35
	v_add_f32_e32 v36, 1.0, v36
	v_add_f32_e32 v37, 1.0, v37
	v_rcp_f32_e32 v30, v30
	v_rcp_f32_e32 v31, v31
	v_rcp_f32_e32 v32, v32
	v_rcp_f32_e32 v33, v33
	v_rcp_f32_e32 v34, v34
	v_rcp_f32_e32 v35, v35
	v_rcp_f32_e32 v36, v36
	v_rcp_f32_e32 v37, v37
	v_pk_mul_f32 v[30:31], v[30:31], v[22:23]
	v_pk_mul_f32 v[32:33], v[32:33], v[24:25]
	v_pk_mul_f32 v[34:35], v[34:35], v[26:27]
	v_pk_mul_f32 v[36:37], v[36:37], v[28:29]
	v_pk_mul_f32 v[140:141], v[140:141], v[30:31]
	v_pk_mul_f32 v[142:143], v[142:143], v[32:33]
	v_pk_mul_f32 v[144:145], v[144:145], v[34:35]
	v_pk_mul_f32 v[194:195], v[194:195], v[36:37]
	v_cvt_pk_bf16_f32 v108, v140, v141
	v_cvt_pk_bf16_f32 v109, v142, v143
	v_cvt_pk_bf16_f32 v110, v144, v145
	v_cvt_pk_bf16_f32 v111, v194, v195
	global_store_dwordx4 v13, v[108:111], s[34:35]
	v_lshlrev_b32_e32 v22, 16, v162
	v_and_b32_e32 v23, 0xffff0000, v162
	v_lshlrev_b32_e32 v24, 16, v163
	v_and_b32_e32 v25, 0xffff0000, v163
	v_lshlrev_b32_e32 v26, 16, v164
	v_and_b32_e32 v27, 0xffff0000, v164
	v_lshlrev_b32_e32 v28, 16, v165
	v_and_b32_e32 v29, 0xffff0000, v165
	v_lshlrev_b32_e32 v30, 16, v166
	v_and_b32_e32 v31, 0xffff0000, v166
	v_lshlrev_b32_e32 v32, 16, v167
	v_and_b32_e32 v33, 0xffff0000, v167
	v_lshlrev_b32_e32 v34, 16, v168
	v_and_b32_e32 v35, 0xffff0000, v168
	v_lshlrev_b32_e32 v36, 16, v169
	v_and_b32_e32 v37, 0xffff0000, v169
	v_pk_mul_f32 v[22:23], v[22:23], v[30:31]
	v_pk_mul_f32 v[24:25], v[24:25], v[32:33]
	v_pk_mul_f32 v[26:27], v[26:27], v[34:35]
	v_pk_mul_f32 v[28:29], v[28:29], v[36:37]
	v_pk_mul_f32 v[244:245], v[212:213], v[18:19] op_sel_hi:[1,0]
	v_pk_mul_f32 v[246:247], v[214:215], v[18:19] op_sel_hi:[1,0]
	v_pk_mul_f32 v[248:249], v[216:217], v[18:19] op_sel_hi:[1,0]
	v_pk_mul_f32 v[4:5], v[218:219], v[18:19] op_sel_hi:[1,0]
	v_pk_fma_f32 v[140:141], v[244:245], v[22:23], 0 op_sel_hi:[1,1,0]
	v_pk_fma_f32 v[142:143], v[246:247], v[24:25], 0 op_sel_hi:[1,1,0]
	v_pk_fma_f32 v[144:145], v[248:249], v[26:27], 0 op_sel_hi:[1,1,0]
	v_pk_fma_f32 v[194:195], v[4:5], v[28:29], 0 op_sel_hi:[1,1,0]
	v_lshlrev_b32_e32 v22, 16, v170
	v_and_b32_e32 v23, 0xffff0000, v170
	v_lshlrev_b32_e32 v24, 16, v171
	v_and_b32_e32 v25, 0xffff0000, v171
	v_lshlrev_b32_e32 v26, 16, v172
	v_and_b32_e32 v27, 0xffff0000, v172
	v_lshlrev_b32_e32 v28, 16, v173
	v_and_b32_e32 v29, 0xffff0000, v173
	v_lshlrev_b32_e32 v30, 16, v174
	v_and_b32_e32 v31, 0xffff0000, v174
	v_lshlrev_b32_e32 v32, 16, v175
	v_and_b32_e32 v33, 0xffff0000, v175
	v_lshlrev_b32_e32 v34, 16, v176
	v_and_b32_e32 v35, 0xffff0000, v176
	v_lshlrev_b32_e32 v36, 16, v177
	v_and_b32_e32 v37, 0xffff0000, v177
	v_pk_mul_f32 v[22:23], v[22:23], v[30:31]
	v_pk_mul_f32 v[24:25], v[24:25], v[32:33]
	v_pk_mul_f32 v[26:27], v[26:27], v[34:35]
	v_pk_mul_f32 v[28:29], v[28:29], v[36:37]
	v_pk_mul_f32 v[244:245], v[220:221], v[20:21] op_sel_hi:[1,0]
	v_pk_mul_f32 v[246:247], v[222:223], v[20:21] op_sel_hi:[1,0]
	v_pk_mul_f32 v[248:249], v[224:225], v[20:21] op_sel_hi:[1,0]
	v_pk_mul_f32 v[4:5], v[226:227], v[20:21] op_sel_hi:[1,0]
	v_pk_fma_f32 v[140:141], v[244:245], v[22:23], v[140:141]
	v_pk_fma_f32 v[142:143], v[246:247], v[24:25], v[142:143]
	v_pk_fma_f32 v[144:145], v[248:249], v[26:27], v[144:145]
	v_pk_fma_f32 v[194:195], v[4:5], v[28:29], v[194:195]
	v_lshlrev_b32_e32 v22, 16, v178
	v_and_b32_e32 v23, 0xffff0000, v178
	v_lshlrev_b32_e32 v24, 16, v179
	v_and_b32_e32 v25, 0xffff0000, v179
	v_lshlrev_b32_e32 v26, 16, v180
	v_and_b32_e32 v27, 0xffff0000, v180
	v_lshlrev_b32_e32 v28, 16, v181
	v_and_b32_e32 v29, 0xffff0000, v181
	v_lshlrev_b32_e32 v30, 16, v182
	v_and_b32_e32 v31, 0xffff0000, v182
	v_lshlrev_b32_e32 v32, 16, v183
	v_and_b32_e32 v33, 0xffff0000, v183
	v_lshlrev_b32_e32 v34, 16, v184
	v_and_b32_e32 v35, 0xffff0000, v184
	v_lshlrev_b32_e32 v36, 16, v185
	v_and_b32_e32 v37, 0xffff0000, v185
	v_pk_mul_f32 v[22:23], v[22:23], v[30:31]
	v_pk_mul_f32 v[24:25], v[24:25], v[32:33]
	v_pk_mul_f32 v[26:27], v[26:27], v[34:35]
	v_pk_mul_f32 v[28:29], v[28:29], v[36:37]
	v_pk_fma_f32 v[140:141], v[228:229], v[22:23], v[140:141]
	v_pk_fma_f32 v[142:143], v[230:231], v[24:25], v[142:143]
	v_pk_fma_f32 v[144:145], v[232:233], v[26:27], v[144:145]
	v_pk_fma_f32 v[194:195], v[234:235], v[28:29], v[194:195]
	v_pk_add_f32 v[140:141], v[236:237], v[140:141]
	v_pk_add_f32 v[142:143], v[238:239], v[142:143]
	v_pk_add_f32 v[144:145], v[240:241], v[144:145]
	v_pk_add_f32 v[194:195], v[242:243], v[194:195]
	v_lshlrev_b32_e32 v30, 16, v186
	v_and_b32_e32 v31, 0xffff0000, v186
	v_lshlrev_b32_e32 v32, 16, v187
	v_and_b32_e32 v33, 0xffff0000, v187
	v_lshlrev_b32_e32 v34, 16, v188
	v_and_b32_e32 v35, 0xffff0000, v188
	v_lshlrev_b32_e32 v36, 16, v189
	v_and_b32_e32 v37, 0xffff0000, v189
	v_lshlrev_b32_e32 v22, 16, v190
	v_and_b32_e32 v23, 0xffff0000, v190
	v_lshlrev_b32_e32 v24, 16, v191
	v_and_b32_e32 v25, 0xffff0000, v191
	v_lshlrev_b32_e32 v26, 16, v192
	v_and_b32_e32 v27, 0xffff0000, v192
	v_lshlrev_b32_e32 v28, 16, v193
	v_and_b32_e32 v29, 0xffff0000, v193
	v_pk_mul_f32 v[140:141], v[140:141], v[30:31]
	v_pk_mul_f32 v[142:143], v[142:143], v[32:33]
	v_pk_mul_f32 v[144:145], v[144:145], v[34:35]
	v_pk_mul_f32 v[194:195], v[194:195], v[36:37]
	v_mul_f32_e32 v30, 0xbfb8aa3b, v22
	v_mul_f32_e32 v31, 0xbfb8aa3b, v23
	v_mul_f32_e32 v32, 0xbfb8aa3b, v24
	v_mul_f32_e32 v33, 0xbfb8aa3b, v25
	v_mul_f32_e32 v34, 0xbfb8aa3b, v26
	v_mul_f32_e32 v35, 0xbfb8aa3b, v27
	v_mul_f32_e32 v36, 0xbfb8aa3b, v28
	v_mul_f32_e32 v37, 0xbfb8aa3b, v29
	v_exp_f32_e32 v30, v30
	v_exp_f32_e32 v31, v31
	v_exp_f32_e32 v32, v32
	v_exp_f32_e32 v33, v33
	v_exp_f32_e32 v34, v34
	v_exp_f32_e32 v35, v35
	v_exp_f32_e32 v36, v36
	v_exp_f32_e32 v37, v37
	v_add_f32_e32 v30, 1.0, v30
	v_add_f32_e32 v31, 1.0, v31
	v_add_f32_e32 v32, 1.0, v32
	v_add_f32_e32 v33, 1.0, v33
	v_add_f32_e32 v34, 1.0, v34
	v_add_f32_e32 v35, 1.0, v35
	v_add_f32_e32 v36, 1.0, v36
	v_add_f32_e32 v37, 1.0, v37
	v_rcp_f32_e32 v30, v30
	v_rcp_f32_e32 v31, v31
	v_rcp_f32_e32 v32, v32
	v_rcp_f32_e32 v33, v33
	v_rcp_f32_e32 v34, v34
	v_rcp_f32_e32 v35, v35
	v_rcp_f32_e32 v36, v36
	v_rcp_f32_e32 v37, v37
	v_pk_mul_f32 v[30:31], v[30:31], v[22:23]
	v_pk_mul_f32 v[32:33], v[32:33], v[24:25]
	v_pk_mul_f32 v[34:35], v[34:35], v[26:27]
	v_pk_mul_f32 v[36:37], v[36:37], v[28:29]
	v_pk_mul_f32 v[140:141], v[140:141], v[30:31]
	v_pk_mul_f32 v[142:143], v[142:143], v[32:33]
	v_pk_mul_f32 v[144:145], v[144:145], v[34:35]
	v_pk_mul_f32 v[194:195], v[194:195], v[36:37]
	v_cvt_pk_bf16_f32 v162, v140, v141
	v_cvt_pk_bf16_f32 v163, v142, v143
	v_cvt_pk_bf16_f32 v164, v144, v145
	v_cvt_pk_bf16_f32 v165, v194, v195
	global_store_dwordx4 v17, v[162:165], s[34:35]
	s_mov_b64 s[2:3], exec

.Lem_b3:
	global_load_dwordx4 v[212:215], v145, s[4:5]
	global_load_dwordx4 v[216:219], v145, s[4:5] offset:256
	s_add_u32 s62, s4, 0x20000
	s_addc_u32 s63, s5, 0
	global_load_dwordx4 v[220:223], v145, s[62:63]
	global_load_dwordx4 v[224:227], v145, s[62:63] offset:256
	s_add_u32 s62, s4, 0x40000
	s_addc_u32 s63, s5, 0
	global_load_dwordx4 v[228:231], v145, s[62:63]
	global_load_dwordx4 v[232:235], v145, s[62:63] offset:256
	s_add_u32 s62, s4, 0x60000
	s_addc_u32 s63, s5, 0
	global_load_dwordx4 v[236:239], v145, s[62:63]
	global_load_dwordx4 v[240:243], v145, s[62:63] offset:256
	s_add_u32 s62, s4, 0x100000
	s_addc_u32 s63, s5, 0
	global_load_dwordx4 v[244:247], v145, s[62:63]
	global_load_dwordx4 v[178:181], v145, s[62:63] offset:256
	s_add_u32 s62, s4, 0x120000
	s_addc_u32 s63, s5, 0
	global_load_dwordx4 v[182:185], v145, s[62:63]
	global_load_dwordx4 v[186:189], v145, s[62:63] offset:256
	s_add_u32 s62, s4, 0x140000
	s_addc_u32 s63, s5, 0
	global_load_dwordx4 v[190:193], v145, s[62:63]
	global_load_dwordx4 v[162:165], v145, s[62:63] offset:256
	s_add_u32 s62, s4, 0x160000
	s_addc_u32 s63, s5, 0
	global_load_dwordx4 v[166:169], v145, s[62:63]
	global_load_dwordx4 v[170:173], v145, s[62:63] offset:256
	s_waitcnt vmcnt(14)
	v_lshlrev_b32_e32 v194, 16, v212
	v_lshlrev_b32_e32 v248, 16, v213
	v_and_b32_e32 v195, 0xffff0000, v212
	v_and_b32_e32 v249, 0xffff0000, v213
	v_pk_mul_f32 v[128:129], v[128:129], v[194:195]
	v_pk_mul_f32 v[130:131], v[130:131], v[248:249]
	v_lshlrev_b32_e32 v194, 16, v214
	v_lshlrev_b32_e32 v248, 16, v215
	v_and_b32_e32 v195, 0xffff0000, v214
	v_and_b32_e32 v249, 0xffff0000, v215
	v_pk_mul_f32 v[124:125], v[124:125], v[194:195]
	v_pk_mul_f32 v[126:127], v[126:127], v[248:249]
	v_cvt_pk_bf16_f32 v212, v128, v129
	v_cvt_pk_bf16_f32 v213, v130, v131
	v_cvt_pk_bf16_f32 v214, v124, v125
	v_cvt_pk_bf16_f32 v215, v126, v127
	global_store_dwordx4 v148, v[212:215], s[30:31]
	v_lshlrev_b32_e32 v194, 16, v216
	v_lshlrev_b32_e32 v248, 16, v217
	v_and_b32_e32 v195, 0xffff0000, v216
	v_and_b32_e32 v249, 0xffff0000, v217
	v_pk_mul_f32 v[96:97], v[96:97], v[194:195]
	v_pk_mul_f32 v[98:99], v[98:99], v[248:249]
	v_lshlrev_b32_e32 v194, 16, v218
	v_lshlrev_b32_e32 v248, 16, v219
	v_and_b32_e32 v195, 0xffff0000, v218
	v_and_b32_e32 v249, 0xffff0000, v219
	v_pk_mul_f32 v[92:93], v[92:93], v[194:195]
	v_pk_mul_f32 v[94:95], v[94:95], v[248:249]
	v_cvt_pk_bf16_f32 v216, v96, v97
	v_cvt_pk_bf16_f32 v217, v98, v99
	v_cvt_pk_bf16_f32 v218, v92, v93
	v_cvt_pk_bf16_f32 v219, v94, v95
	global_store_dwordx4 v148, v[216:219], s[30:31] offset:256
	s_waitcnt vmcnt(12)
	s_add_u32 s62, s30, 0x8000
	s_addc_u32 s63, s31, 0
	v_lshlrev_b32_e32 v194, 16, v220
	v_lshlrev_b32_e32 v248, 16, v221
	v_and_b32_e32 v195, 0xffff0000, v220
	v_and_b32_e32 v249, 0xffff0000, v221
	v_pk_mul_f32 v[120:121], v[120:121], v[194:195]
	v_pk_mul_f32 v[122:123], v[122:123], v[248:249]
	v_lshlrev_b32_e32 v194, 16, v222
	v_lshlrev_b32_e32 v248, 16, v223
	v_and_b32_e32 v195, 0xffff0000, v222
	v_and_b32_e32 v249, 0xffff0000, v223
	v_pk_mul_f32 v[116:117], v[116:117], v[194:195]
	v_pk_mul_f32 v[118:119], v[118:119], v[248:249]
	v_cvt_pk_bf16_f32 v220, v120, v121
	v_cvt_pk_bf16_f32 v221, v122, v123
	v_cvt_pk_bf16_f32 v222, v116, v117
	v_cvt_pk_bf16_f32 v223, v118, v119
	global_store_dwordx4 v148, v[220:223], s[62:63]
	v_lshlrev_b32_e32 v194, 16, v224
	v_lshlrev_b32_e32 v248, 16, v225
	v_and_b32_e32 v195, 0xffff0000, v224
	v_and_b32_e32 v249, 0xffff0000, v225
	v_pk_mul_f32 v[88:89], v[88:89], v[194:195]
	v_pk_mul_f32 v[90:91], v[90:91], v[248:249]
	v_lshlrev_b32_e32 v194, 16, v226
	v_lshlrev_b32_e32 v248, 16, v227
	v_and_b32_e32 v195, 0xffff0000, v226
	v_and_b32_e32 v249, 0xffff0000, v227
	v_pk_mul_f32 v[84:85], v[84:85], v[194:195]
	v_pk_mul_f32 v[86:87], v[86:87], v[248:249]
	v_cvt_pk_bf16_f32 v224, v88, v89
	v_cvt_pk_bf16_f32 v225, v90, v91
	v_cvt_pk_bf16_f32 v226, v84, v85
	v_cvt_pk_bf16_f32 v227, v86, v87
	global_store_dwordx4 v148, v[224:227], s[62:63] offset:256
	s_waitcnt vmcnt(10)
	s_add_u32 s62, s30, 0x10000
	s_addc_u32 s63, s31, 0
	v_lshlrev_b32_e32 v194, 16, v228
	v_lshlrev_b32_e32 v248, 16, v229
	v_and_b32_e32 v195, 0xffff0000, v228
	v_and_b32_e32 v249, 0xffff0000, v229
	v_pk_mul_f32 v[112:113], v[112:113], v[194:195]
	v_pk_mul_f32 v[114:115], v[114:115], v[248:249]
	v_lshlrev_b32_e32 v194, 16, v230
	v_lshlrev_b32_e32 v248, 16, v231
	v_and_b32_e32 v195, 0xffff0000, v230
	v_and_b32_e32 v249, 0xffff0000, v231
	v_pk_mul_f32 v[108:109], v[108:109], v[194:195]
	v_pk_mul_f32 v[110:111], v[110:111], v[248:249]
	v_cvt_pk_bf16_f32 v228, v112, v113
	v_cvt_pk_bf16_f32 v229, v114, v115
	v_cvt_pk_bf16_f32 v230, v108, v109
	v_cvt_pk_bf16_f32 v231, v110, v111
	global_store_dwordx4 v148, v[228:231], s[62:63]
	v_lshlrev_b32_e32 v194, 16, v232
	v_lshlrev_b32_e32 v248, 16, v233
	v_and_b32_e32 v195, 0xffff0000, v232
	v_and_b32_e32 v249, 0xffff0000, v233
	v_pk_mul_f32 v[80:81], v[80:81], v[194:195]
	v_pk_mul_f32 v[82:83], v[82:83], v[248:249]
	v_lshlrev_b32_e32 v194, 16, v234
	v_lshlrev_b32_e32 v248, 16, v235
	v_and_b32_e32 v195, 0xffff0000, v234
	v_and_b32_e32 v249, 0xffff0000, v235
	v_pk_mul_f32 v[76:77], v[76:77], v[194:195]
	v_pk_mul_f32 v[78:79], v[78:79], v[248:249]
	v_cvt_pk_bf16_f32 v232, v80, v81
	v_cvt_pk_bf16_f32 v233, v82, v83
	v_cvt_pk_bf16_f32 v234, v76, v77
	v_cvt_pk_bf16_f32 v235, v78, v79
	global_store_dwordx4 v148, v[232:235], s[62:63] offset:256
	s_waitcnt vmcnt(8)
	s_add_u32 s62, s30, 0x18000
	s_addc_u32 s63, s31, 0
	v_lshlrev_b32_e32 v194, 16, v236
	v_lshlrev_b32_e32 v248, 16, v237
	v_and_b32_e32 v195, 0xffff0000, v236
	v_and_b32_e32 v249, 0xffff0000, v237
	v_pk_mul_f32 v[104:105], v[104:105], v[194:195]
	v_pk_mul_f32 v[106:107], v[106:107], v[248:249]
	v_lshlrev_b32_e32 v194, 16, v238
	v_lshlrev_b32_e32 v248, 16, v239
	v_and_b32_e32 v195, 0xffff0000, v238
	v_and_b32_e32 v249, 0xffff0000, v239
	v_pk_mul_f32 v[100:101], v[100:101], v[194:195]
	v_pk_mul_f32 v[102:103], v[102:103], v[248:249]
	v_cvt_pk_bf16_f32 v236, v104, v105
	v_cvt_pk_bf16_f32 v237, v106, v107
	v_cvt_pk_bf16_f32 v238, v100, v101
	v_cvt_pk_bf16_f32 v239, v102, v103
	global_store_dwordx4 v148, v[236:239], s[62:63]
	v_lshlrev_b32_e32 v194, 16, v240
	v_lshlrev_b32_e32 v248, 16, v241
	v_and_b32_e32 v195, 0xffff0000, v240
	v_and_b32_e32 v249, 0xffff0000, v241
	v_pk_mul_f32 v[72:73], v[72:73], v[194:195]
	v_pk_mul_f32 v[74:75], v[74:75], v[248:249]
	v_lshlrev_b32_e32 v194, 16, v242
	v_lshlrev_b32_e32 v248, 16, v243
	v_and_b32_e32 v195, 0xffff0000, v242
	v_and_b32_e32 v249, 0xffff0000, v243
	v_pk_mul_f32 v[68:69], v[68:69], v[194:195]
	v_pk_mul_f32 v[70:71], v[70:71], v[248:249]
	v_cvt_pk_bf16_f32 v240, v72, v73
	v_cvt_pk_bf16_f32 v241, v74, v75
	v_cvt_pk_bf16_f32 v242, v68, v69
	v_cvt_pk_bf16_f32 v243, v70, v71
	global_store_dwordx4 v148, v[240:243], s[62:63] offset:256
	s_waitcnt vmcnt(6)
	s_add_u32 s62, s30, 0x40000
	s_addc_u32 s63, s31, 0
	v_lshlrev_b32_e32 v194, 16, v244
	v_lshlrev_b32_e32 v248, 16, v245
	v_and_b32_e32 v195, 0xffff0000, v244
	v_and_b32_e32 v249, 0xffff0000, v245
	v_pk_mul_f32 v[64:65], v[64:65], v[194:195]
	v_pk_mul_f32 v[66:67], v[66:67], v[248:249]
	v_lshlrev_b32_e32 v194, 16, v246
	v_lshlrev_b32_e32 v248, 16, v247
	v_and_b32_e32 v195, 0xffff0000, v246
	v_and_b32_e32 v249, 0xffff0000, v247
	v_pk_mul_f32 v[60:61], v[60:61], v[194:195]
	v_pk_mul_f32 v[62:63], v[62:63], v[248:249]
	v_cvt_pk_bf16_f32 v244, v64, v65
	v_cvt_pk_bf16_f32 v245, v66, v67
	v_cvt_pk_bf16_f32 v246, v60, v61
	v_cvt_pk_bf16_f32 v247, v62, v63
	global_store_dwordx4 v148, v[244:247], s[62:63]
	v_lshlrev_b32_e32 v194, 16, v178
	v_lshlrev_b32_e32 v248, 16, v179
	v_and_b32_e32 v195, 0xffff0000, v178
	v_and_b32_e32 v249, 0xffff0000, v179
	v_pk_mul_f32 v[32:33], v[32:33], v[194:195]
	v_pk_mul_f32 v[34:35], v[34:35], v[248:249]
	v_lshlrev_b32_e32 v194, 16, v180
	v_lshlrev_b32_e32 v248, 16, v181
	v_and_b32_e32 v195, 0xffff0000, v180
	v_and_b32_e32 v249, 0xffff0000, v181
	v_pk_mul_f32 v[28:29], v[28:29], v[194:195]
	v_pk_mul_f32 v[30:31], v[30:31], v[248:249]
	v_cvt_pk_bf16_f32 v178, v32, v33
	v_cvt_pk_bf16_f32 v179, v34, v35
	v_cvt_pk_bf16_f32 v180, v28, v29
	v_cvt_pk_bf16_f32 v181, v30, v31
	global_store_dwordx4 v148, v[178:181], s[62:63] offset:256
	s_waitcnt vmcnt(4)
	s_add_u32 s62, s30, 0x48000
	s_addc_u32 s63, s31, 0
	v_lshlrev_b32_e32 v194, 16, v182
	v_lshlrev_b32_e32 v248, 16, v183
	v_and_b32_e32 v195, 0xffff0000, v182
	v_and_b32_e32 v249, 0xffff0000, v183
	v_pk_mul_f32 v[56:57], v[56:57], v[194:195]
	v_pk_mul_f32 v[58:59], v[58:59], v[248:249]
	v_lshlrev_b32_e32 v194, 16, v184
	v_lshlrev_b32_e32 v248, 16, v185
	v_and_b32_e32 v195, 0xffff0000, v184
	v_and_b32_e32 v249, 0xffff0000, v185
	v_pk_mul_f32 v[52:53], v[52:53], v[194:195]
	v_pk_mul_f32 v[54:55], v[54:55], v[248:249]
	v_cvt_pk_bf16_f32 v182, v56, v57
	v_cvt_pk_bf16_f32 v183, v58, v59
	v_cvt_pk_bf16_f32 v184, v52, v53
	v_cvt_pk_bf16_f32 v185, v54, v55
	global_store_dwordx4 v148, v[182:185], s[62:63]
	v_lshlrev_b32_e32 v194, 16, v186
	v_lshlrev_b32_e32 v248, 16, v187
	v_and_b32_e32 v195, 0xffff0000, v186
	v_and_b32_e32 v249, 0xffff0000, v187
	v_pk_mul_f32 v[24:25], v[24:25], v[194:195]
	v_pk_mul_f32 v[26:27], v[26:27], v[248:249]
	v_lshlrev_b32_e32 v194, 16, v188
	v_lshlrev_b32_e32 v248, 16, v189
	v_and_b32_e32 v195, 0xffff0000, v188
	v_and_b32_e32 v249, 0xffff0000, v189
	v_pk_mul_f32 v[20:21], v[20:21], v[194:195]
	v_pk_mul_f32 v[22:23], v[22:23], v[248:249]
	v_cvt_pk_bf16_f32 v186, v24, v25
	v_cvt_pk_bf16_f32 v187, v26, v27
	v_cvt_pk_bf16_f32 v188, v20, v21
	v_cvt_pk_bf16_f32 v189, v22, v23
	global_store_dwordx4 v148, v[186:189], s[62:63] offset:256
	s_waitcnt vmcnt(2)
	s_add_u32 s62, s30, 0x50000
	s_addc_u32 s63, s31, 0
	v_lshlrev_b32_e32 v194, 16, v190
	v_lshlrev_b32_e32 v248, 16, v191
	v_and_b32_e32 v195, 0xffff0000, v190
	v_and_b32_e32 v249, 0xffff0000, v191
	v_pk_mul_f32 v[48:49], v[48:49], v[194:195]
	v_pk_mul_f32 v[50:51], v[50:51], v[248:249]
	v_lshlrev_b32_e32 v194, 16, v192
	v_lshlrev_b32_e32 v248, 16, v193
	v_and_b32_e32 v195, 0xffff0000, v192
	v_and_b32_e32 v249, 0xffff0000, v193
	v_pk_mul_f32 v[44:45], v[44:45], v[194:195]
	v_pk_mul_f32 v[46:47], v[46:47], v[248:249]
	v_cvt_pk_bf16_f32 v190, v48, v49
	v_cvt_pk_bf16_f32 v191, v50, v51
	v_cvt_pk_bf16_f32 v192, v44, v45
	v_cvt_pk_bf16_f32 v193, v46, v47
	global_store_dwordx4 v148, v[190:193], s[62:63]
	v_lshlrev_b32_e32 v194, 16, v162
	v_lshlrev_b32_e32 v248, 16, v163
	v_and_b32_e32 v195, 0xffff0000, v162
	v_and_b32_e32 v249, 0xffff0000, v163
	v_pk_mul_f32 v[16:17], v[16:17], v[194:195]
	v_pk_mul_f32 v[18:19], v[18:19], v[248:249]
	v_lshlrev_b32_e32 v194, 16, v164
	v_lshlrev_b32_e32 v248, 16, v165
	v_and_b32_e32 v195, 0xffff0000, v164
	v_and_b32_e32 v249, 0xffff0000, v165
	v_pk_mul_f32 v[12:13], v[12:13], v[194:195]
	v_pk_mul_f32 v[14:15], v[14:15], v[248:249]
	v_cvt_pk_bf16_f32 v162, v16, v17
	v_cvt_pk_bf16_f32 v163, v18, v19
	v_cvt_pk_bf16_f32 v164, v12, v13
	v_cvt_pk_bf16_f32 v165, v14, v15
	global_store_dwordx4 v148, v[162:165], s[62:63] offset:256
	s_waitcnt vmcnt(0)
	s_add_u32 s62, s30, 0x58000
	s_addc_u32 s63, s31, 0
	v_lshlrev_b32_e32 v194, 16, v166
	v_lshlrev_b32_e32 v248, 16, v167
	v_and_b32_e32 v195, 0xffff0000, v166
	v_and_b32_e32 v249, 0xffff0000, v167
	v_pk_mul_f32 v[40:41], v[40:41], v[194:195]
	v_pk_mul_f32 v[42:43], v[42:43], v[248:249]
	v_lshlrev_b32_e32 v194, 16, v168
	v_lshlrev_b32_e32 v248, 16, v169
	v_and_b32_e32 v195, 0xffff0000, v168
	v_and_b32_e32 v249, 0xffff0000, v169
	v_pk_mul_f32 v[36:37], v[36:37], v[194:195]
	v_pk_mul_f32 v[38:39], v[38:39], v[248:249]
	v_cvt_pk_bf16_f32 v166, v40, v41
	v_cvt_pk_bf16_f32 v167, v42, v43
	v_cvt_pk_bf16_f32 v168, v36, v37
	v_cvt_pk_bf16_f32 v169, v38, v39
	global_store_dwordx4 v148, v[166:169], s[62:63]
	v_lshlrev_b32_e32 v194, 16, v170
	v_lshlrev_b32_e32 v248, 16, v171
	v_and_b32_e32 v195, 0xffff0000, v170
	v_and_b32_e32 v249, 0xffff0000, v171
	v_pk_mul_f32 v[8:9], v[8:9], v[194:195]
	v_pk_mul_f32 v[10:11], v[10:11], v[248:249]
	v_lshlrev_b32_e32 v194, 16, v172
	v_lshlrev_b32_e32 v248, 16, v173
	v_and_b32_e32 v195, 0xffff0000, v172
	v_and_b32_e32 v249, 0xffff0000, v173
	v_pk_mul_f32 v[4:5], v[4:5], v[194:195]
	v_pk_mul_f32 v[6:7], v[6:7], v[248:249]
	v_cvt_pk_bf16_f32 v170, v8, v9
	v_cvt_pk_bf16_f32 v171, v10, v11
	v_cvt_pk_bf16_f32 v172, v4, v5
	v_cvt_pk_bf16_f32 v173, v6, v7
	global_store_dwordx4 v148, v[170:173], s[62:63] offset:256

.LBB0_746:
	v_lshl_add_u32 v172, s84, 8, v180
	v_lshl_or_b32 v173, s83, 8, v182
	v_xor_b32_e32 v176, 16, v207
	v_xor_b32_e32 v177, 32, v207
	v_lshlrev_b32_e32 v175, 10, v172
	v_add_u32_e32 v175, v175, v173
	v_lshlrev_b32_e32 v174, 2, v175
	v_lshlrev_b32_e32 v175, 1, v175
	v_lshlrev_b32_e32 v173, 2, v173
	v_lshlrev_b32_e32 v172, 2, v172
	v_lshlrev_b32_e32 v176, 2, v176
	v_lshlrev_b32_e32 v177, 2, v177
	global_load_dwordx4 v[62:65], v173, s[4:5]
	global_load_dwordx4 v[58:61], v173, s[4:5] offset:16
	global_load_dwordx4 v[46:49], v173, s[4:5] offset:512
	global_load_dwordx4 v[34:37], v173, s[4:5] offset:528
	global_load_dwordx4 v[212:215], v174, s[2:3]
	global_load_dwordx4 v[216:219], v174, s[2:3] offset:16
	global_load_dwordx4 v[220:223], v174, s[2:3] offset:512
	global_load_dwordx4 v[224:227], v174, s[2:3] offset:528
	s_add_u32 s86, s2, 0x10000
	s_addc_u32 s87, s3, 0
	global_load_dwordx4 v[228:231], v174, s[86:87]
	global_load_dwordx4 v[232:235], v174, s[86:87] offset:16
	global_load_dwordx4 v[236:239], v174, s[86:87] offset:512
	global_load_dwordx4 v[240:243], v174, s[86:87] offset:528
	s_add_u32 s86, s2, 0x20000
	s_addc_u32 s87, s3, 0
	global_load_dwordx4 v[184:187], v174, s[86:87]
	global_load_dwordx4 v[188:191], v174, s[86:87] offset:16
	global_load_dwordx4 v[192:195], v174, s[86:87] offset:512
	global_load_dwordx4 v[244:247], v174, s[86:87] offset:528
	s_lshl_b32 s13, s83, 2
	s_or_b32 s50, s13, s78
	s_ashr_i32 s51, s50, 31
	s_lshl_b64 s[50:51], s[50:51], 17
	v_readlane_b32 s60, v251, 55
	v_readlane_b32 s61, v251, 56
	s_nop 3
	s_add_u32 s50, s60, s50
	s_addc_u32 s51, s61, s51
	s_waitcnt vmcnt(8)
	v_pk_add_f32 v[142:143], v[142:143], v[212:213]
	v_pk_add_f32 v[144:145], v[144:145], v[214:215]
	v_pk_add_f32 v[138:139], v[138:139], v[216:217]
	v_pk_add_f32 v[140:141], v[140:141], v[218:219]
	v_pk_add_f32 v[134:135], v[134:135], v[220:221]
	v_pk_add_f32 v[136:137], v[136:137], v[222:223]
	v_pk_add_f32 v[130:131], v[130:131], v[224:225]
	v_pk_add_f32 v[132:133], v[132:133], v[226:227]
	global_store_dwordx4 v174, v[142:145], s[16:17]
	global_store_dwordx4 v174, v[138:141], s[16:17] offset:16
	global_store_dwordx4 v174, v[134:137], s[16:17] offset:512
	global_store_dwordx4 v174, v[130:133], s[16:17] offset:528
	v_mul_f32_e32 v149, v145, v145
	v_mul_f32_e32 v148, v143, v143
	v_fmac_f32_e32 v148, v142, v142
	v_fmac_f32_e32 v149, v144, v144
	v_add_f32_e32 v148, v148, v149
	v_mul_f32_e32 v149, v139, v139
	v_fmac_f32_e32 v149, v138, v138
	v_add_f32_e32 v148, v148, v149
	v_mul_f32_e32 v149, v141, v141
	v_fmac_f32_e32 v149, v140, v140
	v_add_f32_e32 v178, v149, v148
	v_mul_f32_e32 v149, v137, v137
	v_mul_f32_e32 v148, v135, v135
	v_fmac_f32_e32 v148, v134, v134
	v_fmac_f32_e32 v149, v136, v136
	v_add_f32_e32 v148, v148, v149
	v_mul_f32_e32 v149, v131, v131
	v_fmac_f32_e32 v149, v130, v130
	v_add_f32_e32 v148, v148, v149
	v_mul_f32_e32 v149, v133, v133
	v_fmac_f32_e32 v149, v132, v132
	v_add_f32_e32 v148, v149, v148
	v_add_f32_e32 v178, v178, v148
	ds_bpermute_b32 v179, v176, v178
	v_pk_mul_f32 v[212:213], v[62:63], v[142:143]
	v_pk_mul_f32 v[214:215], v[64:65], v[144:145]
	v_pk_mul_f32 v[216:217], v[58:59], v[138:139]
	v_pk_mul_f32 v[218:219], v[60:61], v[140:141]
	v_pk_mul_f32 v[220:221], v[46:47], v[134:135]
	v_pk_mul_f32 v[222:223], v[48:49], v[136:137]
	v_pk_mul_f32 v[224:225], v[34:35], v[130:131]
	v_pk_mul_f32 v[226:227], v[36:37], v[132:133]
	s_waitcnt lgkmcnt(0)
	v_add_f32_e32 v178, v178, v179
	ds_bpermute_b32 v248, v177, v178
	v_cvt_pk_bf16_f32 v212, v212, v213
	v_cvt_pk_bf16_f32 v213, v214, v215
	v_cvt_pk_bf16_f32 v214, v216, v217
	v_cvt_pk_bf16_f32 v215, v218, v219
	v_cvt_pk_bf16_f32 v220, v220, v221
	v_cvt_pk_bf16_f32 v221, v222, v223
	v_cvt_pk_bf16_f32 v222, v224, v225
	v_cvt_pk_bf16_f32 v223, v226, v227
	global_store_dwordx4 v175, v[212:215], s[34:35]
	global_store_dwordx4 v175, v[220:223], s[34:35] offset:256
	s_waitcnt lgkmcnt(0)
	v_add_f32_e32 v178, v178, v248
	s_and_saveexec_b64 s[58:59], s[40:41]
	global_store_dword v172, v178, s[50:51]
	s_or_b64 exec, exec, s[58:59]
	s_add_u32 s86, s2, 0x30000
	s_addc_u32 s87, s3, 0
	global_load_dwordx4 v[212:215], v174, s[86:87]
	global_load_dwordx4 v[216:219], v174, s[86:87] offset:16
	global_load_dwordx4 v[220:223], v174, s[86:87] offset:512
	global_load_dwordx4 v[224:227], v174, s[86:87] offset:528
	s_waitcnt vmcnt(8)
	v_pk_add_f32 v[126:127], v[126:127], v[228:229]
	v_pk_add_f32 v[128:129], v[128:129], v[230:231]
	v_pk_add_f32 v[122:123], v[122:123], v[232:233]
	v_pk_add_f32 v[124:125], v[124:125], v[234:235]
	v_pk_add_f32 v[118:119], v[118:119], v[236:237]
	v_pk_add_f32 v[120:121], v[120:121], v[238:239]
	v_pk_add_f32 v[114:115], v[114:115], v[240:241]
	v_pk_add_f32 v[116:117], v[116:117], v[242:243]
	s_add_u32 s88, s16, 0x10000
	s_addc_u32 s89, s17, 0
	s_add_u32 s90, s34, 0x8000
	s_addc_u32 s91, s35, 0
	global_store_dwordx4 v174, v[126:129], s[88:89]
	global_store_dwordx4 v174, v[122:125], s[88:89] offset:16
	global_store_dwordx4 v174, v[118:121], s[88:89] offset:512
	global_store_dwordx4 v174, v[114:117], s[88:89] offset:528
	v_mul_f32_e32 v149, v129, v129
	v_mul_f32_e32 v148, v127, v127
	v_fmac_f32_e32 v148, v126, v126
	v_fmac_f32_e32 v149, v128, v128
	v_add_f32_e32 v148, v148, v149
	v_mul_f32_e32 v149, v123, v123
	v_fmac_f32_e32 v149, v122, v122
	v_add_f32_e32 v148, v148, v149
	v_mul_f32_e32 v149, v125, v125
	v_fmac_f32_e32 v149, v124, v124
	v_add_f32_e32 v178, v149, v148
	v_mul_f32_e32 v149, v121, v121
	v_mul_f32_e32 v148, v119, v119
	v_fmac_f32_e32 v148, v118, v118
	v_fmac_f32_e32 v149, v120, v120
	v_add_f32_e32 v148, v148, v149
	v_mul_f32_e32 v149, v115, v115
	v_fmac_f32_e32 v149, v114, v114
	v_add_f32_e32 v148, v148, v149
	v_mul_f32_e32 v149, v117, v117
	v_fmac_f32_e32 v149, v116, v116
	v_add_f32_e32 v148, v149, v148
	v_add_f32_e32 v178, v178, v148
	ds_bpermute_b32 v179, v176, v178
	v_pk_mul_f32 v[228:229], v[62:63], v[126:127]
	v_pk_mul_f32 v[230:231], v[64:65], v[128:129]
	v_pk_mul_f32 v[232:233], v[58:59], v[122:123]
	v_pk_mul_f32 v[234:235], v[60:61], v[124:125]
	v_pk_mul_f32 v[236:237], v[46:47], v[118:119]
	v_pk_mul_f32 v[238:239], v[48:49], v[120:121]
	v_pk_mul_f32 v[240:241], v[34:35], v[114:115]
	v_pk_mul_f32 v[242:243], v[36:37], v[116:117]
	s_waitcnt lgkmcnt(0)
	v_add_f32_e32 v178, v178, v179
	ds_bpermute_b32 v248, v177, v178
	v_cvt_pk_bf16_f32 v228, v228, v229
	v_cvt_pk_bf16_f32 v229, v230, v231
	v_cvt_pk_bf16_f32 v230, v232, v233
	v_cvt_pk_bf16_f32 v231, v234, v235
	v_cvt_pk_bf16_f32 v236, v236, v237
	v_cvt_pk_bf16_f32 v237, v238, v239
	v_cvt_pk_bf16_f32 v238, v240, v241
	v_cvt_pk_bf16_f32 v239, v242, v243
	global_store_dwordx4 v175, v[228:231], s[90:91]
	global_store_dwordx4 v175, v[236:239], s[90:91] offset:256
	s_waitcnt lgkmcnt(0)
	v_add_f32_e32 v178, v178, v248
	s_and_saveexec_b64 s[58:59], s[40:41]
	global_store_dword v172, v178, s[50:51] offset:64
	s_or_b64 exec, exec, s[58:59]
	s_add_u32 s86, s2, 0x80000
	s_addc_u32 s87, s3, 0
	global_load_dwordx4 v[228:231], v174, s[86:87]
	global_load_dwordx4 v[232:235], v174, s[86:87] offset:16
	global_load_dwordx4 v[236:239], v174, s[86:87] offset:512
	global_load_dwordx4 v[240:243], v174, s[86:87] offset:528
	s_waitcnt vmcnt(8)
	v_pk_add_f32 v[110:111], v[110:111], v[184:185]
	v_pk_add_f32 v[112:113], v[112:113], v[186:187]
	v_pk_add_f32 v[106:107], v[106:107], v[188:189]
	v_pk_add_f32 v[108:109], v[108:109], v[190:191]
	v_pk_add_f32 v[102:103], v[102:103], v[192:193]
	v_pk_add_f32 v[104:105], v[104:105], v[194:195]
	v_pk_add_f32 v[98:99], v[98:99], v[244:245]
	v_pk_add_f32 v[100:101], v[100:101], v[246:247]
	s_add_u32 s88, s16, 0x20000
	s_addc_u32 s89, s17, 0
	s_add_u32 s90, s34, 0x10000
	s_addc_u32 s91, s35, 0
	global_store_dwordx4 v174, v[110:113], s[88:89]
	global_store_dwordx4 v174, v[106:109], s[88:89] offset:16
	global_store_dwordx4 v174, v[102:105], s[88:89] offset:512
	global_store_dwordx4 v174, v[98:101], s[88:89] offset:528
	v_mul_f32_e32 v149, v113, v113
	v_mul_f32_e32 v148, v111, v111
	v_fmac_f32_e32 v148, v110, v110
	v_fmac_f32_e32 v149, v112, v112
	v_add_f32_e32 v148, v148, v149
	v_mul_f32_e32 v149, v107, v107
	v_fmac_f32_e32 v149, v106, v106
	v_add_f32_e32 v148, v148, v149
	v_mul_f32_e32 v149, v109, v109
	v_fmac_f32_e32 v149, v108, v108
	v_add_f32_e32 v178, v149, v148
	v_mul_f32_e32 v149, v105, v105
	v_mul_f32_e32 v148, v103, v103
	v_fmac_f32_e32 v148, v102, v102
	v_fmac_f32_e32 v149, v104, v104
	v_add_f32_e32 v148, v148, v149
	v_mul_f32_e32 v149, v99, v99
	v_fmac_f32_e32 v149, v98, v98
	v_add_f32_e32 v148, v148, v149
	v_mul_f32_e32 v149, v101, v101
	v_fmac_f32_e32 v149, v100, v100
	v_add_f32_e32 v148, v149, v148
	v_add_f32_e32 v178, v178, v148
	ds_bpermute_b32 v179, v176, v178
	v_pk_mul_f32 v[184:185], v[62:63], v[110:111]
	v_pk_mul_f32 v[186:187], v[64:65], v[112:113]
	v_pk_mul_f32 v[188:189], v[58:59], v[106:107]
	v_pk_mul_f32 v[190:191], v[60:61], v[108:109]
	v_pk_mul_f32 v[192:193], v[46:47], v[102:103]
	v_pk_mul_f32 v[194:195], v[48:49], v[104:105]
	v_pk_mul_f32 v[244:245], v[34:35], v[98:99]
	v_pk_mul_f32 v[246:247], v[36:37], v[100:101]
	s_waitcnt lgkmcnt(0)
	v_add_f32_e32 v178, v178, v179
	ds_bpermute_b32 v248, v177, v178
	v_cvt_pk_bf16_f32 v184, v184, v185
	v_cvt_pk_bf16_f32 v185, v186, v187
	v_cvt_pk_bf16_f32 v186, v188, v189
	v_cvt_pk_bf16_f32 v187, v190, v191
	v_cvt_pk_bf16_f32 v192, v192, v193
	v_cvt_pk_bf16_f32 v193, v194, v195
	v_cvt_pk_bf16_f32 v194, v244, v245
	v_cvt_pk_bf16_f32 v195, v246, v247
	global_store_dwordx4 v175, v[184:187], s[90:91]
	global_store_dwordx4 v175, v[192:195], s[90:91] offset:256
	s_waitcnt lgkmcnt(0)
	v_add_f32_e32 v178, v178, v248
	s_and_saveexec_b64 s[58:59], s[40:41]
	global_store_dword v172, v178, s[50:51] offset:128
	s_or_b64 exec, exec, s[58:59]
	s_add_u32 s86, s2, 0x90000
	s_addc_u32 s87, s3, 0
	global_load_dwordx4 v[184:187], v174, s[86:87]
	global_load_dwordx4 v[188:191], v174, s[86:87] offset:16
	global_load_dwordx4 v[192:195], v174, s[86:87] offset:512
	global_load_dwordx4 v[244:247], v174, s[86:87] offset:528
	s_waitcnt vmcnt(8)
	v_pk_add_f32 v[94:95], v[94:95], v[212:213]
	v_pk_add_f32 v[96:97], v[96:97], v[214:215]
	v_pk_add_f32 v[90:91], v[90:91], v[216:217]
	v_pk_add_f32 v[92:93], v[92:93], v[218:219]
	v_pk_add_f32 v[86:87], v[86:87], v[220:221]
	v_pk_add_f32 v[88:89], v[88:89], v[222:223]
	v_pk_add_f32 v[82:83], v[82:83], v[224:225]
	v_pk_add_f32 v[84:85], v[84:85], v[226:227]
	s_add_u32 s88, s16, 0x30000
	s_addc_u32 s89, s17, 0
	s_add_u32 s90, s34, 0x18000
	s_addc_u32 s91, s35, 0
	global_store_dwordx4 v174, v[94:97], s[88:89]
	global_store_dwordx4 v174, v[90:93], s[88:89] offset:16
	global_store_dwordx4 v174, v[86:89], s[88:89] offset:512
	global_store_dwordx4 v174, v[82:85], s[88:89] offset:528
	v_mul_f32_e32 v149, v97, v97
	v_mul_f32_e32 v148, v95, v95
	v_fmac_f32_e32 v148, v94, v94
	v_fmac_f32_e32 v149, v96, v96
	v_add_f32_e32 v148, v148, v149
	v_mul_f32_e32 v149, v91, v91
	v_fmac_f32_e32 v149, v90, v90
	v_add_f32_e32 v148, v148, v149
	v_mul_f32_e32 v149, v93, v93
	v_fmac_f32_e32 v149, v92, v92
	v_add_f32_e32 v178, v149, v148
	v_mul_f32_e32 v149, v89, v89
	v_mul_f32_e32 v148, v87, v87
	v_fmac_f32_e32 v148, v86, v86
	v_fmac_f32_e32 v149, v88, v88
	v_add_f32_e32 v148, v148, v149
	v_mul_f32_e32 v149, v83, v83
	v_fmac_f32_e32 v149, v82, v82
	v_add_f32_e32 v148, v148, v149
	v_mul_f32_e32 v149, v85, v85
	v_fmac_f32_e32 v149, v84, v84
	v_add_f32_e32 v148, v149, v148
	v_add_f32_e32 v178, v178, v148
	ds_bpermute_b32 v179, v176, v178
	v_pk_mul_f32 v[212:213], v[62:63], v[94:95]
	v_pk_mul_f32 v[214:215], v[64:65], v[96:97]
	v_pk_mul_f32 v[216:217], v[58:59], v[90:91]
	v_pk_mul_f32 v[218:219], v[60:61], v[92:93]
	v_pk_mul_f32 v[220:221], v[46:47], v[86:87]
	v_pk_mul_f32 v[222:223], v[48:49], v[88:89]
	v_pk_mul_f32 v[224:225], v[34:35], v[82:83]
	v_pk_mul_f32 v[226:227], v[36:37], v[84:85]
	s_waitcnt lgkmcnt(0)
	v_add_f32_e32 v178, v178, v179
	ds_bpermute_b32 v248, v177, v178
	v_cvt_pk_bf16_f32 v212, v212, v213
	v_cvt_pk_bf16_f32 v213, v214, v215
	v_cvt_pk_bf16_f32 v214, v216, v217
	v_cvt_pk_bf16_f32 v215, v218, v219
	v_cvt_pk_bf16_f32 v220, v220, v221
	v_cvt_pk_bf16_f32 v221, v222, v223
	v_cvt_pk_bf16_f32 v222, v224, v225
	v_cvt_pk_bf16_f32 v223, v226, v227
	global_store_dwordx4 v175, v[212:215], s[90:91]
	global_store_dwordx4 v175, v[220:223], s[90:91] offset:256
	s_waitcnt lgkmcnt(0)
	v_add_f32_e32 v178, v178, v248
	s_and_saveexec_b64 s[58:59], s[40:41]
	global_store_dword v172, v178, s[50:51] offset:192
	s_or_b64 exec, exec, s[58:59]
	s_add_u32 s86, s2, 0xa0000
	s_addc_u32 s87, s3, 0
	global_load_dwordx4 v[212:215], v174, s[86:87]
	global_load_dwordx4 v[216:219], v174, s[86:87] offset:16
	global_load_dwordx4 v[220:223], v174, s[86:87] offset:512
	global_load_dwordx4 v[224:227], v174, s[86:87] offset:528
	s_waitcnt vmcnt(8)
	v_pk_add_f32 v[78:79], v[78:79], v[228:229]
	v_pk_add_f32 v[80:81], v[80:81], v[230:231]
	v_pk_add_f32 v[74:75], v[74:75], v[232:233]
	v_pk_add_f32 v[76:77], v[76:77], v[234:235]
	v_pk_add_f32 v[70:71], v[70:71], v[236:237]
	v_pk_add_f32 v[72:73], v[72:73], v[238:239]
	v_pk_add_f32 v[66:67], v[66:67], v[240:241]
	v_pk_add_f32 v[68:69], v[68:69], v[242:243]
	s_add_u32 s88, s16, 0x80000
	s_addc_u32 s89, s17, 0
	s_add_u32 s90, s34, 0x40000
	s_addc_u32 s91, s35, 0
	global_store_dwordx4 v174, v[78:81], s[88:89]
	global_store_dwordx4 v174, v[74:77], s[88:89] offset:16
	global_store_dwordx4 v174, v[70:73], s[88:89] offset:512
	global_store_dwordx4 v174, v[66:69], s[88:89] offset:528
	v_mul_f32_e32 v149, v81, v81
	v_mul_f32_e32 v148, v79, v79
	v_fmac_f32_e32 v148, v78, v78
	v_fmac_f32_e32 v149, v80, v80
	v_add_f32_e32 v148, v148, v149
	v_mul_f32_e32 v149, v75, v75
	v_fmac_f32_e32 v149, v74, v74
	v_add_f32_e32 v148, v148, v149
	v_mul_f32_e32 v149, v77, v77
	v_fmac_f32_e32 v149, v76, v76
	v_add_f32_e32 v178, v149, v148
	v_mul_f32_e32 v149, v73, v73
	v_mul_f32_e32 v148, v71, v71
	v_fmac_f32_e32 v148, v70, v70
	v_fmac_f32_e32 v149, v72, v72
	v_add_f32_e32 v148, v148, v149
	v_mul_f32_e32 v149, v67, v67
	v_fmac_f32_e32 v149, v66, v66
	v_add_f32_e32 v148, v148, v149
	v_mul_f32_e32 v149, v69, v69
	v_fmac_f32_e32 v149, v68, v68
	v_add_f32_e32 v148, v149, v148
	v_add_f32_e32 v178, v178, v148
	ds_bpermute_b32 v179, v176, v178
	v_pk_mul_f32 v[228:229], v[62:63], v[78:79]
	v_pk_mul_f32 v[230:231], v[64:65], v[80:81]
	v_pk_mul_f32 v[232:233], v[58:59], v[74:75]
	v_pk_mul_f32 v[234:235], v[60:61], v[76:77]
	v_pk_mul_f32 v[236:237], v[46:47], v[70:71]
	v_pk_mul_f32 v[238:239], v[48:49], v[72:73]
	v_pk_mul_f32 v[240:241], v[34:35], v[66:67]
	v_pk_mul_f32 v[242:243], v[36:37], v[68:69]
	s_waitcnt lgkmcnt(0)
	v_add_f32_e32 v178, v178, v179
	ds_bpermute_b32 v248, v177, v178
	v_cvt_pk_bf16_f32 v228, v228, v229
	v_cvt_pk_bf16_f32 v229, v230, v231
	v_cvt_pk_bf16_f32 v230, v232, v233
	v_cvt_pk_bf16_f32 v231, v234, v235
	v_cvt_pk_bf16_f32 v236, v236, v237
	v_cvt_pk_bf16_f32 v237, v238, v239
	v_cvt_pk_bf16_f32 v238, v240, v241
	v_cvt_pk_bf16_f32 v239, v242, v243
	global_store_dwordx4 v175, v[228:231], s[90:91]
	global_store_dwordx4 v175, v[236:239], s[90:91] offset:256
	s_waitcnt lgkmcnt(0)
	v_add_f32_e32 v178, v178, v248
	s_and_saveexec_b64 s[58:59], s[40:41]
	global_store_dword v172, v178, s[50:51] offset:512
	s_or_b64 exec, exec, s[58:59]
	s_add_u32 s86, s2, 0xb0000
	s_addc_u32 s87, s3, 0
	global_load_dwordx4 v[228:231], v174, s[86:87]
	global_load_dwordx4 v[232:235], v174, s[86:87] offset:16
	global_load_dwordx4 v[236:239], v174, s[86:87] offset:512
	global_load_dwordx4 v[240:243], v174, s[86:87] offset:528
	s_waitcnt vmcnt(8)
	v_pk_add_f32 v[54:55], v[54:55], v[184:185]
	v_pk_add_f32 v[56:57], v[56:57], v[186:187]
	v_pk_add_f32 v[50:51], v[50:51], v[188:189]
	v_pk_add_f32 v[52:53], v[52:53], v[190:191]
	v_pk_add_f32 v[42:43], v[42:43], v[192:193]
	v_pk_add_f32 v[44:45], v[44:45], v[194:195]
	v_pk_add_f32 v[38:39], v[38:39], v[244:245]
	v_pk_add_f32 v[40:41], v[40:41], v[246:247]
	s_add_u32 s88, s16, 0x90000
	s_addc_u32 s89, s17, 0
	s_add_u32 s90, s34, 0x48000
	s_addc_u32 s91, s35, 0
	global_store_dwordx4 v174, v[54:57], s[88:89]
	global_store_dwordx4 v174, v[50:53], s[88:89] offset:16
	global_store_dwordx4 v174, v[42:45], s[88:89] offset:512
	global_store_dwordx4 v174, v[38:41], s[88:89] offset:528
	v_mul_f32_e32 v149, v57, v57
	v_mul_f32_e32 v148, v55, v55
	v_fmac_f32_e32 v148, v54, v54
	v_fmac_f32_e32 v149, v56, v56
	v_add_f32_e32 v148, v148, v149
	v_mul_f32_e32 v149, v51, v51
	v_fmac_f32_e32 v149, v50, v50
	v_add_f32_e32 v148, v148, v149
	v_mul_f32_e32 v149, v53, v53
	v_fmac_f32_e32 v149, v52, v52
	v_add_f32_e32 v178, v149, v148
	v_mul_f32_e32 v149, v45, v45
	v_mul_f32_e32 v148, v43, v43
	v_fmac_f32_e32 v148, v42, v42
	v_fmac_f32_e32 v149, v44, v44
	v_add_f32_e32 v148, v148, v149
	v_mul_f32_e32 v149, v39, v39
	v_fmac_f32_e32 v149, v38, v38
	v_add_f32_e32 v148, v148, v149
	v_mul_f32_e32 v149, v41, v41
	v_fmac_f32_e32 v149, v40, v40
	v_add_f32_e32 v148, v149, v148
	v_add_f32_e32 v178, v178, v148
	ds_bpermute_b32 v179, v176, v178
	v_pk_mul_f32 v[184:185], v[62:63], v[54:55]
	v_pk_mul_f32 v[186:187], v[64:65], v[56:57]
	v_pk_mul_f32 v[188:189], v[58:59], v[50:51]
	v_pk_mul_f32 v[190:191], v[60:61], v[52:53]
	v_pk_mul_f32 v[192:193], v[46:47], v[42:43]
	v_pk_mul_f32 v[194:195], v[48:49], v[44:45]
	v_pk_mul_f32 v[244:245], v[34:35], v[38:39]
	v_pk_mul_f32 v[246:247], v[36:37], v[40:41]
	s_waitcnt lgkmcnt(0)
	v_add_f32_e32 v178, v178, v179
	ds_bpermute_b32 v248, v177, v178
	v_cvt_pk_bf16_f32 v184, v184, v185
	v_cvt_pk_bf16_f32 v185, v186, v187
	v_cvt_pk_bf16_f32 v186, v188, v189
	v_cvt_pk_bf16_f32 v187, v190, v191
	v_cvt_pk_bf16_f32 v192, v192, v193
	v_cvt_pk_bf16_f32 v193, v194, v195
	v_cvt_pk_bf16_f32 v194, v244, v245
	v_cvt_pk_bf16_f32 v195, v246, v247
	global_store_dwordx4 v175, v[184:187], s[90:91]
	global_store_dwordx4 v175, v[192:195], s[90:91] offset:256
	s_waitcnt lgkmcnt(0)
	v_add_f32_e32 v178, v178, v248
	s_and_saveexec_b64 s[58:59], s[40:41]
	global_store_dword v172, v178, s[50:51] offset:576
	s_or_b64 exec, exec, s[58:59]
	s_waitcnt vmcnt(4)
	v_pk_add_f32 v[30:31], v[30:31], v[212:213]
	v_pk_add_f32 v[32:33], v[32:33], v[214:215]
	v_pk_add_f32 v[26:27], v[26:27], v[216:217]
	v_pk_add_f32 v[28:29], v[28:29], v[218:219]
	v_pk_add_f32 v[22:23], v[22:23], v[220:221]
	v_pk_add_f32 v[24:25], v[24:25], v[222:223]
	v_pk_add_f32 v[18:19], v[18:19], v[224:225]
	v_pk_add_f32 v[20:21], v[20:21], v[226:227]
	s_add_u32 s88, s16, 0xa0000
	s_addc_u32 s89, s17, 0
	s_add_u32 s90, s34, 0x50000
	s_addc_u32 s91, s35, 0
	global_store_dwordx4 v174, v[30:33], s[88:89]
	global_store_dwordx4 v174, v[26:29], s[88:89] offset:16
	global_store_dwordx4 v174, v[22:25], s[88:89] offset:512
	global_store_dwordx4 v174, v[18:21], s[88:89] offset:528
	v_mul_f32_e32 v149, v33, v33
	v_mul_f32_e32 v148, v31, v31
	v_fmac_f32_e32 v148, v30, v30
	v_fmac_f32_e32 v149, v32, v32
	v_add_f32_e32 v148, v148, v149
	v_mul_f32_e32 v149, v27, v27
	v_fmac_f32_e32 v149, v26, v26
	v_add_f32_e32 v148, v148, v149
	v_mul_f32_e32 v149, v29, v29
	v_fmac_f32_e32 v149, v28, v28
	v_add_f32_e32 v178, v149, v148
	v_mul_f32_e32 v149, v25, v25
	v_mul_f32_e32 v148, v23, v23
	v_fmac_f32_e32 v148, v22, v22
	v_fmac_f32_e32 v149, v24, v24
	v_add_f32_e32 v148, v148, v149
	v_mul_f32_e32 v149, v19, v19
	v_fmac_f32_e32 v149, v18, v18
	v_add_f32_e32 v148, v148, v149
	v_mul_f32_e32 v149, v21, v21
	v_fmac_f32_e32 v149, v20, v20
	v_add_f32_e32 v148, v149, v148
	v_add_f32_e32 v178, v178, v148
	ds_bpermute_b32 v179, v176, v178
	v_pk_mul_f32 v[212:213], v[62:63], v[30:31]
	v_pk_mul_f32 v[214:215], v[64:65], v[32:33]
	v_pk_mul_f32 v[216:217], v[58:59], v[26:27]
	v_pk_mul_f32 v[218:219], v[60:61], v[28:29]
	v_pk_mul_f32 v[220:221], v[46:47], v[22:23]
	v_pk_mul_f32 v[222:223], v[48:49], v[24:25]
	v_pk_mul_f32 v[224:225], v[34:35], v[18:19]
	v_pk_mul_f32 v[226:227], v[36:37], v[20:21]
	s_waitcnt lgkmcnt(0)
	v_add_f32_e32 v178, v178, v179
	ds_bpermute_b32 v248, v177, v178
	v_cvt_pk_bf16_f32 v212, v212, v213
	v_cvt_pk_bf16_f32 v213, v214, v215
	v_cvt_pk_bf16_f32 v214, v216, v217
	v_cvt_pk_bf16_f32 v215, v218, v219
	v_cvt_pk_bf16_f32 v220, v220, v221
	v_cvt_pk_bf16_f32 v221, v222, v223
	v_cvt_pk_bf16_f32 v222, v224, v225
	v_cvt_pk_bf16_f32 v223, v226, v227
	global_store_dwordx4 v175, v[212:215], s[90:91]
	global_store_dwordx4 v175, v[220:223], s[90:91] offset:256
	s_waitcnt lgkmcnt(0)
	v_add_f32_e32 v178, v178, v248
	s_and_saveexec_b64 s[58:59], s[40:41]
	global_store_dword v172, v178, s[50:51] offset:640
	s_or_b64 exec, exec, s[58:59]
	s_waitcnt vmcnt(0)
	v_pk_add_f32 v[14:15], v[14:15], v[228:229]
	v_pk_add_f32 v[16:17], v[16:17], v[230:231]
	v_pk_add_f32 v[10:11], v[10:11], v[232:233]
	v_pk_add_f32 v[12:13], v[12:13], v[234:235]
	v_pk_add_f32 v[6:7], v[6:7], v[236:237]
	v_pk_add_f32 v[8:9], v[8:9], v[238:239]
	v_pk_add_f32 v[2:3], v[2:3], v[240:241]
	v_pk_add_f32 v[4:5], v[4:5], v[242:243]
	s_add_u32 s88, s16, 0xb0000
	s_addc_u32 s89, s17, 0
	s_add_u32 s90, s34, 0x58000
	s_addc_u32 s91, s35, 0
	global_store_dwordx4 v174, v[14:17], s[88:89]
	global_store_dwordx4 v174, v[10:13], s[88:89] offset:16
	global_store_dwordx4 v174, v[6:9], s[88:89] offset:512
	global_store_dwordx4 v174, v[2:5], s[88:89] offset:528
	v_mul_f32_e32 v149, v17, v17
	v_mul_f32_e32 v148, v15, v15
	v_fmac_f32_e32 v148, v14, v14
	v_fmac_f32_e32 v149, v16, v16
	v_add_f32_e32 v148, v148, v149
	v_mul_f32_e32 v149, v11, v11
	v_fmac_f32_e32 v149, v10, v10
	v_add_f32_e32 v148, v148, v149
	v_mul_f32_e32 v149, v13, v13
	v_fmac_f32_e32 v149, v12, v12
	v_add_f32_e32 v178, v149, v148
	v_mul_f32_e32 v149, v9, v9
	v_mul_f32_e32 v148, v7, v7
	v_fmac_f32_e32 v148, v6, v6
	v_fmac_f32_e32 v149, v8, v8
	v_add_f32_e32 v148, v148, v149
	v_mul_f32_e32 v149, v3, v3
	v_fmac_f32_e32 v149, v2, v2
	v_add_f32_e32 v148, v148, v149
	v_mul_f32_e32 v149, v5, v5
	v_fmac_f32_e32 v149, v4, v4
	v_add_f32_e32 v148, v149, v148
	v_add_f32_e32 v178, v178, v148
	ds_bpermute_b32 v179, v176, v178
	v_pk_mul_f32 v[228:229], v[62:63], v[14:15]
	v_pk_mul_f32 v[230:231], v[64:65], v[16:17]
	v_pk_mul_f32 v[232:233], v[58:59], v[10:11]
	v_pk_mul_f32 v[234:235], v[60:61], v[12:13]
	v_pk_mul_f32 v[236:237], v[46:47], v[6:7]
	v_pk_mul_f32 v[238:239], v[48:49], v[8:9]
	v_pk_mul_f32 v[240:241], v[34:35], v[2:3]
	v_pk_mul_f32 v[242:243], v[36:37], v[4:5]
	s_waitcnt lgkmcnt(0)
	v_add_f32_e32 v178, v178, v179
	ds_bpermute_b32 v248, v177, v178
	v_cvt_pk_bf16_f32 v228, v228, v229
	v_cvt_pk_bf16_f32 v229, v230, v231
	v_cvt_pk_bf16_f32 v230, v232, v233
	v_cvt_pk_bf16_f32 v231, v234, v235
	v_cvt_pk_bf16_f32 v236, v236, v237
	v_cvt_pk_bf16_f32 v237, v238, v239
	v_cvt_pk_bf16_f32 v238, v240, v241
	v_cvt_pk_bf16_f32 v239, v242, v243
	global_store_dwordx4 v175, v[228:231], s[90:91]
	global_store_dwordx4 v175, v[236:239], s[90:91] offset:256
	s_waitcnt lgkmcnt(0)
	v_add_f32_e32 v178, v178, v248
	s_and_saveexec_b64 s[58:59], s[40:41]
	global_store_dword v172, v178, s[50:51] offset:704
	s_or_b64 exec, exec, s[58:59]
	s_andn2_b64 vcc, exec, s[42:43]
	s_mov_b64 s[42:43], -1
	s_cbranch_vccnz .LBB0_734
	s_andn2_b64 vcc, exec, s[0:1]
	s_cbranch_vccnz .LBB0_733
	s_barrier
	s_branch .LBB0_733
